# Q also stored fragment-major (phase-1 Q epilogue, phase-2 loader, scan loads)
# speedup vs baseline: 1.0574x; 1.0122x over previous
.LBB0_208:
	s_add_i32 s27, s5, 64
	s_min_u32 s30, s27, 0x3e0
	s_lshl_b32 s30, s30, 1
	v_lshl_add_u64 v[180:181], v[154:155], 0, s[30:31]
	v_lshl_add_u64 v[184:185], v[158:159], 0, s[30:31]
	v_lshl_add_u64 v[188:189], v[160:161], 0, s[30:31]
	v_lshl_add_u64 v[192:193], v[162:163], 0, s[30:31]
	v_lshl_add_u64 v[196:197], v[156:157], 0, s[30:31]
	v_lshl_add_u64 v[200:201], v[164:165], 0, s[30:31]
	global_load_dwordx4 v[180:183], v[180:181], off
	ds_read_b128 v[204:207], v178 offset:32768
	global_load_dwordx4 v[184:187], v[184:185], off
	ds_read_b128 v[208:211], v178 offset:33792
	global_load_dwordx4 v[188:191], v[188:189], off
	ds_read_b128 v[212:215], v178 offset:34816
	global_load_dwordx4 v[192:195], v[192:193], off
	ds_read_b128 v[216:219], v178 offset:35840
	global_load_dwordx4 v[196:199], v[196:197], off
	ds_read_b128 v[222:225], v176
	global_load_dwordx4 v[200:203], v[200:201], off
	ds_read_b128 v[226:229], v176 offset:1024
	ds_read_b128 v[230:233], v176 offset:2048
	ds_read_b128 v[234:237], v176 offset:3072
	ds_read_b128 v[238:241], v176 offset:4096
	ds_read_b128 v[242:245], v176 offset:5120
	ds_read_b128 v[246:249], v176 offset:6144
	ds_read_b128 v[250:253], v176 offset:7168
	s_setprio 1
	s_waitcnt lgkmcnt(7)
	v_mfma_f32_16x16x32_bf16 v[124:127], v[222:225], v[204:207], v[124:127]
	v_mfma_f32_16x16x32_bf16 v[120:123], v[222:225], v[208:211], v[120:123]
	v_mfma_f32_16x16x32_bf16 v[60:63], v[222:225], v[212:215], v[60:63]
	v_mfma_f32_16x16x32_bf16 v[56:59], v[222:225], v[216:219], v[56:59]
	s_waitcnt lgkmcnt(6)
	v_mfma_f32_16x16x32_bf16 v[116:119], v[226:229], v[204:207], v[116:119]
	v_mfma_f32_16x16x32_bf16 v[112:115], v[226:229], v[208:211], v[112:115]
	v_mfma_f32_16x16x32_bf16 v[52:55], v[226:229], v[212:215], v[52:55]
	v_mfma_f32_16x16x32_bf16 v[48:51], v[226:229], v[216:219], v[48:51]
	s_waitcnt lgkmcnt(5)
	v_mfma_f32_16x16x32_bf16 v[108:111], v[230:233], v[204:207], v[108:111]
	v_mfma_f32_16x16x32_bf16 v[104:107], v[230:233], v[208:211], v[104:107]
	v_mfma_f32_16x16x32_bf16 v[44:47], v[230:233], v[212:215], v[44:47]
	v_mfma_f32_16x16x32_bf16 v[40:43], v[230:233], v[216:219], v[40:43]
	s_waitcnt lgkmcnt(4)
	v_mfma_f32_16x16x32_bf16 v[100:103], v[234:237], v[204:207], v[100:103]
	v_mfma_f32_16x16x32_bf16 v[96:99], v[234:237], v[208:211], v[96:99]
	v_mfma_f32_16x16x32_bf16 v[36:39], v[234:237], v[212:215], v[36:39]
	v_mfma_f32_16x16x32_bf16 v[32:35], v[234:237], v[216:219], v[32:35]
	s_waitcnt lgkmcnt(3)
	v_mfma_f32_16x16x32_bf16 v[92:95], v[238:241], v[204:207], v[92:95]
	v_mfma_f32_16x16x32_bf16 v[88:91], v[238:241], v[208:211], v[88:91]
	v_mfma_f32_16x16x32_bf16 v[28:31], v[238:241], v[212:215], v[28:31]
	v_mfma_f32_16x16x32_bf16 v[24:27], v[238:241], v[216:219], v[24:27]
	s_waitcnt lgkmcnt(2)
	v_mfma_f32_16x16x32_bf16 v[84:87], v[242:245], v[204:207], v[84:87]
	v_mfma_f32_16x16x32_bf16 v[80:83], v[242:245], v[208:211], v[80:83]
	v_mfma_f32_16x16x32_bf16 v[20:23], v[242:245], v[212:215], v[20:23]
	v_mfma_f32_16x16x32_bf16 v[16:19], v[242:245], v[216:219], v[16:19]
	s_waitcnt lgkmcnt(1)
	v_mfma_f32_16x16x32_bf16 v[76:79], v[246:249], v[204:207], v[76:79]
	v_mfma_f32_16x16x32_bf16 v[72:75], v[246:249], v[208:211], v[72:75]
	v_mfma_f32_16x16x32_bf16 v[12:15], v[246:249], v[212:215], v[12:15]
	v_mfma_f32_16x16x32_bf16 v[8:11], v[246:249], v[216:219], v[8:11]
	s_waitcnt lgkmcnt(0)
	v_mfma_f32_16x16x32_bf16 v[68:71], v[250:253], v[204:207], v[68:71]
	v_mfma_f32_16x16x32_bf16 v[64:67], v[250:253], v[208:211], v[64:67]
	v_mfma_f32_16x16x32_bf16 v[4:7], v[250:253], v[212:215], v[4:7]
	v_mfma_f32_16x16x32_bf16 v[0:3], v[250:253], v[216:219], v[0:3]
	s_setprio 0
	s_min_u32 s5, s5, 0x380
	s_lshl_b32 s30, s5, 1
	s_mov_b32 s53, s31
	s_add_i32 s52, s30, 0xc0
	s_waitcnt vmcnt(11)
	ds_write_b128 v152, v[128:131] offset:16384
	s_waitcnt vmcnt(9)
	ds_write_b128 v152, v[136:139] offset:20480
	s_waitcnt vmcnt(8)
	ds_write_b128 v152, v[140:143] offset:24576
	s_waitcnt vmcnt(7)
	ds_write_b128 v152, v[144:147] offset:28672
	s_waitcnt vmcnt(7)
	ds_write_b128 v152, v[132:135] offset:40960
	s_waitcnt vmcnt(6)
	ds_write_b128 v152, v[148:151] offset:45056
	v_lshl_add_u64 v[128:129], v[154:155], 0, s[30:31]
	v_lshl_add_u64 v[132:133], v[156:157], 0, s[30:31]
	v_lshl_add_u64 v[136:137], v[158:159], 0, s[52:53]
	v_lshl_add_u64 v[140:141], v[160:161], 0, s[52:53]
	v_lshl_add_u64 v[144:145], v[162:163], 0, s[52:53]
	v_lshl_add_u64 v[148:149], v[164:165], 0, s[52:53]
	s_waitcnt lgkmcnt(0)
	s_barrier
	global_load_dwordx4 v[128:131], v[128:129], off offset:192
	ds_read_b128 v[204:207], v175 offset:40960
	global_load_dwordx4 v[132:135], v[132:133], off offset:192
	ds_read_b128 v[208:211], v175 offset:41984
	global_load_dwordx4 v[136:139], v[136:137], off
	ds_read_b128 v[212:215], v175 offset:43008
	global_load_dwordx4 v[140:143], v[140:141], off
	ds_read_b128 v[216:219], v175 offset:44032
	global_load_dwordx4 v[144:147], v[144:145], off
	ds_read_b128 v[222:225], v177
	global_load_dwordx4 v[148:151], v[148:149], off
	ds_read_b128 v[226:229], v177 offset:1024
	ds_read_b128 v[230:233], v177 offset:2048
	ds_read_b128 v[234:237], v177 offset:3072
	ds_read_b128 v[238:241], v177 offset:4096
	ds_read_b128 v[242:245], v177 offset:5120
	ds_read_b128 v[246:249], v177 offset:6144
	ds_read_b128 v[250:253], v177 offset:7168
	s_setprio 1
	s_waitcnt lgkmcnt(7)
	v_mfma_f32_16x16x32_bf16 v[124:127], v[222:225], v[204:207], v[124:127]
	v_mfma_f32_16x16x32_bf16 v[120:123], v[222:225], v[208:211], v[120:123]
	v_mfma_f32_16x16x32_bf16 v[60:63], v[222:225], v[212:215], v[60:63]
	v_mfma_f32_16x16x32_bf16 v[56:59], v[222:225], v[216:219], v[56:59]
	s_waitcnt lgkmcnt(6)
	v_mfma_f32_16x16x32_bf16 v[116:119], v[226:229], v[204:207], v[116:119]
	v_mfma_f32_16x16x32_bf16 v[112:115], v[226:229], v[208:211], v[112:115]
	v_mfma_f32_16x16x32_bf16 v[52:55], v[226:229], v[212:215], v[52:55]
	v_mfma_f32_16x16x32_bf16 v[48:51], v[226:229], v[216:219], v[48:51]
	s_waitcnt lgkmcnt(5)
	v_mfma_f32_16x16x32_bf16 v[108:111], v[230:233], v[204:207], v[108:111]
	v_mfma_f32_16x16x32_bf16 v[104:107], v[230:233], v[208:211], v[104:107]
	v_mfma_f32_16x16x32_bf16 v[44:47], v[230:233], v[212:215], v[44:47]
	v_mfma_f32_16x16x32_bf16 v[40:43], v[230:233], v[216:219], v[40:43]
	s_waitcnt lgkmcnt(4)
	v_mfma_f32_16x16x32_bf16 v[100:103], v[234:237], v[204:207], v[100:103]
	v_mfma_f32_16x16x32_bf16 v[96:99], v[234:237], v[208:211], v[96:99]
	v_mfma_f32_16x16x32_bf16 v[36:39], v[234:237], v[212:215], v[36:39]
	v_mfma_f32_16x16x32_bf16 v[32:35], v[234:237], v[216:219], v[32:35]
	s_waitcnt lgkmcnt(3)
	v_mfma_f32_16x16x32_bf16 v[92:95], v[238:241], v[204:207], v[92:95]
	v_mfma_f32_16x16x32_bf16 v[88:91], v[238:241], v[208:211], v[88:91]
	v_mfma_f32_16x16x32_bf16 v[28:31], v[238:241], v[212:215], v[28:31]
	v_mfma_f32_16x16x32_bf16 v[24:27], v[238:241], v[216:219], v[24:27]
	s_waitcnt lgkmcnt(2)
	v_mfma_f32_16x16x32_bf16 v[84:87], v[242:245], v[204:207], v[84:87]
	v_mfma_f32_16x16x32_bf16 v[80:83], v[242:245], v[208:211], v[80:83]
	v_mfma_f32_16x16x32_bf16 v[20:23], v[242:245], v[212:215], v[20:23]
	v_mfma_f32_16x16x32_bf16 v[16:19], v[242:245], v[216:219], v[16:19]
	s_waitcnt lgkmcnt(1)
	v_mfma_f32_16x16x32_bf16 v[76:79], v[246:249], v[204:207], v[76:79]
	v_mfma_f32_16x16x32_bf16 v[72:75], v[246:249], v[208:211], v[72:75]
	v_mfma_f32_16x16x32_bf16 v[12:15], v[246:249], v[212:215], v[12:15]
	v_mfma_f32_16x16x32_bf16 v[8:11], v[246:249], v[216:219], v[8:11]
	s_waitcnt lgkmcnt(0)
	v_mfma_f32_16x16x32_bf16 v[68:71], v[250:253], v[204:207], v[68:71]
	v_mfma_f32_16x16x32_bf16 v[64:67], v[250:253], v[208:211], v[64:67]
	v_mfma_f32_16x16x32_bf16 v[4:7], v[250:253], v[212:215], v[4:7]
	v_mfma_f32_16x16x32_bf16 v[0:3], v[250:253], v[216:219], v[0:3]
	s_setprio 0
	s_add_i32 s1, s1, 2
	s_cmp_lt_u32 s1, 30
	s_mov_b32 s5, s27
	s_waitcnt vmcnt(11)
	ds_write_b128 v152, v[180:183]
	s_waitcnt vmcnt(10)
	ds_write_b128 v152, v[184:187] offset:4096
	s_waitcnt vmcnt(9)
	ds_write_b128 v152, v[188:191] offset:8192
	s_waitcnt vmcnt(8)
	ds_write_b128 v152, v[192:195] offset:12288
	s_waitcnt vmcnt(7)
	ds_write_b128 v152, v[196:199] offset:32768
	s_waitcnt vmcnt(6)
	ds_write_b128 v152, v[200:203] offset:36864
	s_waitcnt lgkmcnt(0)
	s_barrier
	s_cbranch_scc1 .LBB0_208
	s_waitcnt vmcnt(5)
	v_mov_b32_e32 v128, v220
	s_cmp_gt_i32 s26, 15
	v_and_b32_e32 v158, 15, v128
	v_and_b32_e32 v160, 64, v128
	v_and_b32_e32 v129, 0xffffff80, v128
	v_lshrrev_b32_e32 v128, 2, v128
	v_add_u32_e32 v130, s4, v129
	v_and_b32_e32 v159, 12, v128
	s_waitcnt vmcnt(3)
	v_or_b32_e32 v136, v130, v159
	v_ashrrev_i32_e32 v128, 14, v130
	s_waitcnt vmcnt(0)
	v_or_b32_e32 v150, 16, v136
	v_or_b32_e32 v148, 32, v136
	v_or_b32_e32 v146, 48, v136
	v_or_b32_e32 v142, 64, v136
	v_or_b32_e32 v140, 0x50, v136
	v_or_b32_e32 v138, 0x60, v136
	v_or_b32_e32 v134, 0x70, v136
	s_mov_b64 s[4:5], -1
	v_ashrrev_i32_e32 v137, 31, v136
	v_lshlrev_b32_e32 v132, 1, v159
	v_mov_b32_e32 v250, s0
	v_and_b32_e32 v250, 0x80, v250
	v_add_u32_e32 v250, v250, v160
	v_mul_u32_u24_e32 v250, 30, v250
	v_lshrrev_b32_e32 v251, 3, v158
	v_mul_u32_u24_e32 v251, 0xf0, v251
	v_add_u32_e32 v250, v250, v251
	v_lshrrev_b32_e32 v251, 2, v159
	v_mul_u32_u24_e32 v251, 0x7c0, v251
	v_sub_u32_e32 v250, v250, v251
	v_ashrrev_i32_e32 v251, 31, v250
	v_and_b32_e32 v252, 8, v159
	v_lshlrev_b32_e32 v252, 5, v252
	v_and_b32_e32 v253, 4, v159
	v_lshl_or_b32 v252, v253, 1, v252
	v_lshl_or_b32 v252, v158, 4, v252
	v_mov_b32_e32 v253, 0
	v_ashrrev_i32_e32 v129, 31, v128
	v_ashrrev_i32_e32 v151, 31, v150
	v_ashrrev_i32_e32 v149, 31, v148
	v_ashrrev_i32_e32 v147, 31, v146
	v_ashrrev_i32_e32 v143, 31, v142
	v_ashrrev_i32_e32 v141, 31, v140
	v_ashrrev_i32_e32 v139, 31, v138
	v_ashrrev_i32_e32 v135, 31, v134
	s_cbranch_scc0 .LBB0_211
	v_lshl_add_u64 v[144:145], v[136:137], 2, s[8:9]
	global_load_dwordx4 v[162:165], v[144:145], off
	s_add_i32 s1, s0, 0xfffff800
	s_and_b32 s5, s0, 0x180
	s_ashr_i32 s4, s1, 9
	v_or_b32_e32 v154, s5, v160
	s_ashr_i32 s5, s4, 31
	v_lshlrev_b64 v[144:145], 9, v[128:129]
	s_lshl_b64 s[4:5], s[4:5], 7
	v_lshrrev_b32_e32 v152, 7, v130
	v_lshl_add_u64 v[130:131], v[144:145], 0, s[4:5]
	v_and_or_b32 v130, v152, s38, v130
	v_lshlrev_b64 v[130:131], 16, v[130:131]
	v_mov_b32_e32 v133, v153
	v_lshl_or_b32 v130, v154, 7, v130
	v_lshl_add_u64 v[178:179], s[12:13], 0, v[252:253]
	v_mov_b32_e32 v145, v131
	v_mov_b32_e32 v181, v131
	v_lshlrev_b64 v[156:157], 1, v[130:131]
	v_or_b32_e32 v144, 0x800, v130
	v_or_b32_e32 v180, 0x1000, v130
	v_or_b32_e32 v130, 0x1800, v130
	v_lshl_add_u64 v[182:183], v[178:179], 0, v[156:157]
	v_lshlrev_b64 v[154:155], 1, v[144:145]
	v_lshlrev_b64 v[144:145], 1, v[180:181]
	v_lshlrev_b64 v[130:131], 1, v[130:131]
	v_lshl_add_u64 v[176:177], v[150:151], 2, s[8:9]
	v_lshl_add_u64 v[180:181], v[178:179], 0, v[154:155]
	v_lshl_add_u64 v[184:185], v[178:179], 0, v[144:145]
	v_lshl_add_u64 v[178:179], v[178:179], 0, v[130:131]
	s_waitcnt vmcnt(0)
	v_mul_f32_e32 v133, v124, v162
	v_mul_f32_e32 v152, v125, v163
	v_mul_f32_e32 v161, v126, v164
	v_mul_f32_e32 v175, v127, v165
	v_mul_f32_e32 v186, v120, v162
	v_mul_f32_e32 v187, v121, v163
	v_mul_f32_e32 v188, v122, v164
	v_mul_f32_e32 v189, v123, v165
	v_mul_f32_e32 v190, v60, v162
	v_mul_f32_e32 v191, v61, v163
	v_mul_f32_e32 v194, v56, v162
	v_mul_f32_e32 v195, v57, v163
	v_cvt_pk_bf16_f32 v162, v133, v152
	v_cvt_pk_bf16_f32 v163, v161, v175
	v_mul_f32_e32 v192, v62, v164
	v_mul_f32_e32 v193, v63, v165
	v_mul_f32_e32 v196, v58, v164
	v_mul_f32_e32 v197, v59, v165
	v_cvt_pk_bf16_f32 v164, v186, v187
	v_cvt_pk_bf16_f32 v165, v188, v189
	v_cvt_pk_bf16_f32 v186, v190, v191
	v_cvt_pk_bf16_f32 v187, v192, v193
	v_cvt_pk_bf16_f32 v188, v194, v195
	v_cvt_pk_bf16_f32 v189, v196, v197
	global_store_dwordx2 v[182:183], v[162:163], off
	global_store_dwordx2 v[180:181], v[164:165], off
	global_store_dwordx2 v[184:185], v[186:187], off
	global_store_dwordx2 v[178:179], v[188:189], off
	global_load_dwordx4 v[162:165], v[176:177], off
	v_bitop3_b32 v133, v136, 28, 16 bitop3:0xc8
	v_lshlrev_b32_e32 v152, 1, v133
	v_lshl_add_u64 v[178:179], s[12:13], 0, v[252:253]
	v_lshl_add_u64 v[180:181], v[178:179], 0, v[156:157]
	v_lshl_add_u64 v[176:177], v[148:149], 2, s[8:9]
	v_lshl_add_u64 v[182:183], v[178:179], 0, v[154:155]
	v_lshl_add_u64 v[184:185], v[178:179], 0, v[144:145]
	v_lshl_add_u64 v[178:179], v[178:179], 0, v[130:131]
	s_waitcnt vmcnt(0)
	v_mul_f32_e32 v133, v116, v162
	v_mul_f32_e32 v152, v117, v163
	v_mul_f32_e32 v161, v118, v164
	v_mul_f32_e32 v175, v119, v165
	v_mul_f32_e32 v186, v112, v162
	v_mul_f32_e32 v187, v113, v163
	v_mul_f32_e32 v188, v114, v164
	v_mul_f32_e32 v189, v115, v165
	v_mul_f32_e32 v190, v52, v162
	v_mul_f32_e32 v191, v53, v163
	v_mul_f32_e32 v194, v48, v162
	v_mul_f32_e32 v195, v49, v163
	v_cvt_pk_bf16_f32 v162, v133, v152
	v_cvt_pk_bf16_f32 v163, v161, v175
	v_mul_f32_e32 v192, v54, v164
	v_mul_f32_e32 v193, v55, v165
	v_mul_f32_e32 v196, v50, v164
	v_mul_f32_e32 v197, v51, v165
	v_cvt_pk_bf16_f32 v164, v186, v187
	v_cvt_pk_bf16_f32 v165, v188, v189
	v_cvt_pk_bf16_f32 v186, v190, v191
	v_cvt_pk_bf16_f32 v187, v192, v193
	v_cvt_pk_bf16_f32 v188, v194, v195
	v_cvt_pk_bf16_f32 v189, v196, v197
	global_store_dwordx2 v[180:181], v[162:163], off offset:512
	global_store_dwordx2 v[182:183], v[164:165], off offset:512
	global_store_dwordx2 v[184:185], v[186:187], off offset:512
	global_store_dwordx2 v[178:179], v[188:189], off offset:512
	global_load_dwordx4 v[162:165], v[176:177], off
	v_bitop3_b32 v133, v136, 44, 32 bitop3:0xc8
	v_lshlrev_b32_e32 v152, 1, v133
	v_lshl_add_u64 v[178:179], s[12:13], 0, v[252:253]
	v_lshl_add_u64 v[180:181], v[178:179], 0, v[156:157]
	v_lshl_add_u64 v[176:177], v[146:147], 2, s[8:9]
	v_lshl_add_u64 v[182:183], v[178:179], 0, v[154:155]
	v_lshl_add_u64 v[184:185], v[178:179], 0, v[144:145]
	v_lshl_add_u64 v[178:179], v[178:179], 0, v[130:131]
	s_waitcnt vmcnt(0)
	v_mul_f32_e32 v133, v108, v162
	v_mul_f32_e32 v152, v109, v163
	v_mul_f32_e32 v161, v110, v164
	v_mul_f32_e32 v175, v111, v165
	v_mul_f32_e32 v186, v104, v162
	v_mul_f32_e32 v187, v105, v163
	v_mul_f32_e32 v188, v106, v164
	v_mul_f32_e32 v189, v107, v165
	v_mul_f32_e32 v190, v44, v162
	v_mul_f32_e32 v191, v45, v163
	v_mul_f32_e32 v194, v40, v162
	v_mul_f32_e32 v195, v41, v163
	v_cvt_pk_bf16_f32 v162, v133, v152
	v_cvt_pk_bf16_f32 v163, v161, v175
	v_mul_f32_e32 v192, v46, v164
	v_mul_f32_e32 v193, v47, v165
	v_mul_f32_e32 v196, v42, v164
	v_mul_f32_e32 v197, v43, v165
	v_cvt_pk_bf16_f32 v164, v186, v187
	v_cvt_pk_bf16_f32 v165, v188, v189
	v_cvt_pk_bf16_f32 v186, v190, v191
	v_cvt_pk_bf16_f32 v187, v192, v193
	v_cvt_pk_bf16_f32 v188, v194, v195
	v_cvt_pk_bf16_f32 v189, v196, v197
	global_store_dwordx2 v[180:181], v[162:163], off offset:1024
	global_store_dwordx2 v[182:183], v[164:165], off offset:1024
	global_store_dwordx2 v[184:185], v[186:187], off offset:1024
	global_store_dwordx2 v[178:179], v[188:189], off offset:1024
	global_load_dwordx4 v[162:165], v[176:177], off
	v_bitop3_b32 v133, v136, 60, 48 bitop3:0xc8
	v_lshlrev_b32_e32 v152, 1, v133
	v_lshl_add_u64 v[178:179], s[12:13], 0, v[252:253]
	v_lshl_add_u64 v[180:181], v[178:179], 0, v[156:157]
	v_lshl_add_u64 v[176:177], v[142:143], 2, s[8:9]
	v_lshl_add_u64 v[182:183], v[178:179], 0, v[154:155]
	v_lshl_add_u64 v[184:185], v[178:179], 0, v[144:145]
	v_lshl_add_u64 v[178:179], v[178:179], 0, v[130:131]
	s_waitcnt vmcnt(0)
	v_mul_f32_e32 v133, v100, v162
	v_mul_f32_e32 v152, v101, v163
	v_mul_f32_e32 v161, v102, v164
	v_mul_f32_e32 v175, v103, v165
	v_mul_f32_e32 v186, v96, v162
	v_mul_f32_e32 v187, v97, v163
	v_mul_f32_e32 v188, v98, v164
	v_mul_f32_e32 v189, v99, v165
	v_mul_f32_e32 v190, v36, v162
	v_mul_f32_e32 v191, v37, v163
	v_mul_f32_e32 v194, v32, v162
	v_mul_f32_e32 v195, v33, v163
	v_cvt_pk_bf16_f32 v162, v133, v152
	v_cvt_pk_bf16_f32 v163, v161, v175
	v_mul_f32_e32 v192, v38, v164
	v_mul_f32_e32 v193, v39, v165
	v_mul_f32_e32 v196, v34, v164
	v_mul_f32_e32 v197, v35, v165
	v_cvt_pk_bf16_f32 v164, v186, v187
	v_cvt_pk_bf16_f32 v165, v188, v189
	v_cvt_pk_bf16_f32 v186, v190, v191
	v_cvt_pk_bf16_f32 v187, v192, v193
	v_cvt_pk_bf16_f32 v188, v194, v195
	v_cvt_pk_bf16_f32 v189, v196, v197
	global_store_dwordx2 v[180:181], v[162:163], off offset:1536
	global_store_dwordx2 v[182:183], v[164:165], off offset:1536
	global_store_dwordx2 v[184:185], v[186:187], off offset:1536
	global_store_dwordx2 v[178:179], v[188:189], off offset:1536
	global_load_dwordx4 v[162:165], v[176:177], off
	v_bitop3_b32 v133, v136, s39, 64 bitop3:0xc8
	v_lshlrev_b32_e32 v152, 1, v133
	v_lshl_add_u64 v[178:179], s[12:13], 0, v[252:253]
	v_lshl_add_u64 v[180:181], v[178:179], 0, v[156:157]
	v_lshl_add_u64 v[176:177], v[140:141], 2, s[8:9]
	v_lshl_add_u64 v[182:183], v[178:179], 0, v[154:155]
	v_lshl_add_u64 v[184:185], v[178:179], 0, v[144:145]
	v_lshl_add_u64 v[178:179], v[178:179], 0, v[130:131]
	s_waitcnt vmcnt(0)
	v_mul_f32_e32 v133, v92, v162
	v_mul_f32_e32 v152, v93, v163
	v_mul_f32_e32 v161, v94, v164
	v_mul_f32_e32 v175, v95, v165
	v_mul_f32_e32 v186, v88, v162
	v_mul_f32_e32 v187, v89, v163
	v_mul_f32_e32 v188, v90, v164
	v_mul_f32_e32 v189, v91, v165
	v_mul_f32_e32 v190, v28, v162
	v_mul_f32_e32 v191, v29, v163
	v_mul_f32_e32 v194, v24, v162
	v_mul_f32_e32 v195, v25, v163
	v_cvt_pk_bf16_f32 v162, v133, v152
	v_cvt_pk_bf16_f32 v163, v161, v175
	v_mul_f32_e32 v192, v30, v164
	v_mul_f32_e32 v193, v31, v165
	v_mul_f32_e32 v196, v26, v164
	v_mul_f32_e32 v197, v27, v165
	v_cvt_pk_bf16_f32 v164, v186, v187
	v_cvt_pk_bf16_f32 v165, v188, v189
	v_cvt_pk_bf16_f32 v186, v190, v191
	v_cvt_pk_bf16_f32 v187, v192, v193
	v_cvt_pk_bf16_f32 v188, v194, v195
	v_cvt_pk_bf16_f32 v189, v196, v197
	global_store_dwordx2 v[180:181], v[162:163], off offset:2048
	global_store_dwordx2 v[182:183], v[164:165], off offset:2048
	global_store_dwordx2 v[184:185], v[186:187], off offset:2048
	global_store_dwordx2 v[178:179], v[188:189], off offset:2048
	global_load_dwordx4 v[162:165], v[176:177], off
	v_bitop3_b32 v133, v136, s40, v166 bitop3:0xc8
	v_lshlrev_b32_e32 v152, 1, v133
	v_lshl_add_u64 v[178:179], s[12:13], 0, v[252:253]
	v_lshl_add_u64 v[180:181], v[178:179], 0, v[156:157]
	v_lshl_add_u64 v[176:177], v[138:139], 2, s[8:9]
	v_lshl_add_u64 v[182:183], v[178:179], 0, v[154:155]
	v_lshl_add_u64 v[184:185], v[178:179], 0, v[144:145]
	v_lshl_add_u64 v[178:179], v[178:179], 0, v[130:131]
	s_waitcnt vmcnt(0)
	v_mul_f32_e32 v133, v84, v162
	v_mul_f32_e32 v152, v85, v163
	v_mul_f32_e32 v161, v86, v164
	v_mul_f32_e32 v175, v87, v165
	v_mul_f32_e32 v186, v80, v162
	v_mul_f32_e32 v187, v81, v163
	v_mul_f32_e32 v188, v82, v164
	v_mul_f32_e32 v189, v83, v165
	v_mul_f32_e32 v190, v20, v162
	v_mul_f32_e32 v191, v21, v163
	v_mul_f32_e32 v194, v16, v162
	v_mul_f32_e32 v195, v17, v163
	v_cvt_pk_bf16_f32 v162, v133, v152
	v_cvt_pk_bf16_f32 v163, v161, v175
	v_mul_f32_e32 v192, v22, v164
	v_mul_f32_e32 v193, v23, v165
	v_mul_f32_e32 v196, v18, v164
	v_mul_f32_e32 v197, v19, v165
	v_cvt_pk_bf16_f32 v164, v186, v187
	v_cvt_pk_bf16_f32 v165, v188, v189
	v_cvt_pk_bf16_f32 v186, v190, v191
	v_cvt_pk_bf16_f32 v187, v192, v193
	v_cvt_pk_bf16_f32 v188, v194, v195
	v_cvt_pk_bf16_f32 v189, v196, v197
	global_store_dwordx2 v[180:181], v[162:163], off offset:2560
	global_store_dwordx2 v[182:183], v[164:165], off offset:2560
	global_store_dwordx2 v[184:185], v[186:187], off offset:2560
	global_store_dwordx2 v[178:179], v[188:189], off offset:2560
	global_load_dwordx4 v[162:165], v[176:177], off
	v_bitop3_b32 v133, v136, s41, v167 bitop3:0xc8
	v_lshlrev_b32_e32 v152, 1, v133
	v_lshl_add_u64 v[178:179], s[12:13], 0, v[252:253]
	v_lshl_add_u64 v[180:181], v[178:179], 0, v[156:157]
	v_lshl_add_u64 v[176:177], v[134:135], 2, s[8:9]
	v_lshl_add_u64 v[182:183], v[178:179], 0, v[154:155]
	v_lshl_add_u64 v[184:185], v[178:179], 0, v[144:145]
	v_lshl_add_u64 v[178:179], v[178:179], 0, v[130:131]
	s_waitcnt vmcnt(0)
	v_mul_f32_e32 v133, v76, v162
	v_mul_f32_e32 v152, v77, v163
	v_mul_f32_e32 v161, v78, v164
	v_mul_f32_e32 v175, v79, v165
	v_mul_f32_e32 v186, v72, v162
	v_mul_f32_e32 v187, v73, v163
	v_mul_f32_e32 v188, v74, v164
	v_mul_f32_e32 v189, v75, v165
	v_mul_f32_e32 v190, v12, v162
	v_mul_f32_e32 v191, v13, v163
	v_mul_f32_e32 v194, v8, v162
	v_mul_f32_e32 v195, v9, v163
	v_cvt_pk_bf16_f32 v162, v133, v152
	v_cvt_pk_bf16_f32 v163, v161, v175
	v_mul_f32_e32 v192, v14, v164
	v_mul_f32_e32 v193, v15, v165
	v_mul_f32_e32 v196, v10, v164
	v_mul_f32_e32 v197, v11, v165
	v_cvt_pk_bf16_f32 v164, v186, v187
	v_cvt_pk_bf16_f32 v165, v188, v189
	v_cvt_pk_bf16_f32 v186, v190, v191
	v_cvt_pk_bf16_f32 v187, v192, v193
	v_cvt_pk_bf16_f32 v188, v194, v195
	v_cvt_pk_bf16_f32 v189, v196, v197
	global_store_dwordx2 v[180:181], v[162:163], off offset:3072
	global_store_dwordx2 v[182:183], v[164:165], off offset:3072
	global_store_dwordx2 v[184:185], v[186:187], off offset:3072
	global_store_dwordx2 v[178:179], v[188:189], off offset:3072
	global_load_dwordx4 v[162:165], v[176:177], off
	v_bitop3_b32 v133, v136, s42, v168 bitop3:0xc8
	v_lshlrev_b32_e32 v152, 1, v133
	v_lshl_add_u64 v[176:177], s[12:13], 0, v[252:253]
	v_lshl_add_u64 v[156:157], v[176:177], 0, v[156:157]
	v_lshl_add_u64 v[154:155], v[176:177], 0, v[154:155]
	v_lshl_add_u64 v[144:145], v[176:177], 0, v[144:145]
	v_lshl_add_u64 v[130:131], v[176:177], 0, v[130:131]
	s_waitcnt vmcnt(0)
	v_mul_f32_e32 v133, v68, v162
	v_mul_f32_e32 v152, v69, v163
	v_mul_f32_e32 v161, v70, v164
	v_mul_f32_e32 v175, v71, v165
	v_mul_f32_e32 v176, v64, v162
	v_mul_f32_e32 v177, v65, v163
	v_mul_f32_e32 v178, v66, v164
	v_mul_f32_e32 v179, v67, v165
	v_mul_f32_e32 v180, v4, v162
	v_mul_f32_e32 v181, v5, v163
	v_mul_f32_e32 v184, v0, v162
	v_mul_f32_e32 v185, v1, v163
	v_cvt_pk_bf16_f32 v162, v133, v152
	v_cvt_pk_bf16_f32 v163, v161, v175
	v_mul_f32_e32 v182, v6, v164
	v_mul_f32_e32 v183, v7, v165
	v_mul_f32_e32 v186, v2, v164
	v_mul_f32_e32 v187, v3, v165
	v_cvt_pk_bf16_f32 v164, v176, v177
	v_cvt_pk_bf16_f32 v165, v178, v179
	v_cvt_pk_bf16_f32 v176, v180, v181
	v_cvt_pk_bf16_f32 v177, v182, v183
	v_cvt_pk_bf16_f32 v178, v184, v185
	v_cvt_pk_bf16_f32 v179, v186, v187
	global_store_dwordx2 v[156:157], v[162:163], off offset:3584
	global_store_dwordx2 v[154:155], v[164:165], off offset:3584
	global_store_dwordx2 v[144:145], v[176:177], off offset:3584
	global_store_dwordx2 v[130:131], v[178:179], off offset:3584
	s_cbranch_execnz .LBB0_206
	s_branch .LBB0_212

.LBB0_214:
	s_andn2_b64 vcc, exec, s[4:5]
	v_lshl_add_u64 v[124:125], s[14:15], 0, v[120:121]
	s_cbranch_vccnz .LBB0_216
	v_bfe_u32 v120, v157, 16, 1
	v_add3_u32 v133, v157, v120, s47
	v_lshl_add_u64 v[120:121], v[124:125], 0, v[152:153]
	v_lshl_add_u64 v[120:121], v[120:121], 0, v[250:251]
	global_store_short_d16_hi v[120:121], v133, off
	v_bfe_u32 v133, v155, 16, 1
	v_add3_u32 v133, v155, v133, s47
	global_store_short_d16_hi v[120:121], v133, off offset:512
	v_bfe_u32 v133, v163, 16, 1
	v_add3_u32 v133, v163, v133, s47
	global_store_short_d16_hi v[120:121], v133, off offset:16
	v_bfe_u32 v133, v161, 16, 1
	v_add3_u32 v133, v161, v133, s47
	global_store_short_d16_hi v[120:121], v133, off offset:528
	v_bfe_u32 v133, v176, 16, 1
	v_add3_u32 v133, v176, v133, s47
	global_store_short_d16_hi v[120:121], v133, off offset:32
	v_bfe_u32 v133, v126, 16, 1
	v_add3_u32 v126, v126, v133, s47
	global_store_short_d16_hi v[120:121], v126, off offset:544
	v_bfe_u32 v126, v179, 16, 1
	v_add3_u32 v126, v179, v126, s47
	global_store_short_d16_hi v[120:121], v126, off offset:48
	v_bfe_u32 v126, v127, 16, 1
	v_add3_u32 v126, v127, v126, s47
	global_store_short_d16_hi v[120:121], v126, off offset:560

.LBB0_218:
	s_andn2_b64 vcc, exec, s[26:27]
	v_lshl_add_u64 v[116:117], s[14:15], 0, v[150:151]
	s_cbranch_vccnz .LBB0_220
	v_bfe_u32 v113, v180, 16, 1
	v_add3_u32 v113, v180, v113, s47
	v_lshl_add_u64 v[150:151], v[116:117], 0, v[152:153]
	v_lshl_add_u64 v[150:151], v[150:151], 0, v[250:251]
	global_store_short_d16_hi v[150:151], v113, off
	v_bfe_u32 v113, v133, 16, 1
	v_add3_u32 v113, v133, v113, s47
	global_store_short_d16_hi v[150:151], v113, off offset:512
	v_bfe_u32 v113, v179, 16, 1
	v_add3_u32 v113, v179, v113, s47
	global_store_short_d16_hi v[150:151], v113, off offset:16
	v_bfe_u32 v113, v118, 16, 1
	v_add3_u32 v113, v118, v113, s47
	global_store_short_d16_hi v[150:151], v113, off offset:528
	v_bfe_u32 v113, v176, 16, 1
	v_add3_u32 v113, v176, v113, s47
	global_store_short_d16_hi v[150:151], v113, off offset:32
	v_bfe_u32 v113, v115, 16, 1
	v_add3_u32 v113, v115, v113, s47
	global_store_short_d16_hi v[150:151], v113, off offset:544
	v_bfe_u32 v113, v119, 16, 1
	v_add3_u32 v113, v119, v113, s47
	global_store_short_d16_hi v[150:151], v113, off offset:48
	v_bfe_u32 v113, v114, 16, 1
	v_add3_u32 v113, v114, v113, s47
	global_store_short_d16_hi v[150:151], v113, off offset:560

.LBB0_222:
	s_andn2_b64 vcc, exec, s[0:1]
	v_lshl_add_u64 v[108:109], s[14:15], 0, v[148:149]
	s_cbranch_vccnz .LBB0_224
	v_bfe_u32 v105, v187, 16, 1
	v_add3_u32 v105, v187, v105, s47
	v_lshl_add_u64 v[148:149], v[108:109], 0, v[152:153]
	v_lshl_add_u64 v[148:149], v[148:149], 0, v[250:251]
	global_store_short_d16_hi v[148:149], v105, off
	v_bfe_u32 v105, v113, 16, 1
	v_add3_u32 v105, v113, v105, s47
	global_store_short_d16_hi v[148:149], v105, off offset:512
	v_bfe_u32 v105, v182, 16, 1
	v_add3_u32 v105, v182, v105, s47
	global_store_short_d16_hi v[148:149], v105, off offset:16
	v_bfe_u32 v105, v110, 16, 1
	v_add3_u32 v105, v110, v105, s47
	global_store_short_d16_hi v[148:149], v105, off offset:528
	v_bfe_u32 v105, v133, 16, 1
	v_add3_u32 v105, v133, v105, s47
	global_store_short_d16_hi v[148:149], v105, off offset:32
	v_bfe_u32 v105, v107, 16, 1
	v_add3_u32 v105, v107, v105, s47
	global_store_short_d16_hi v[148:149], v105, off offset:544
	v_bfe_u32 v105, v111, 16, 1
	v_add3_u32 v105, v111, v105, s47
	global_store_short_d16_hi v[148:149], v105, off offset:48
	v_bfe_u32 v105, v106, 16, 1
	v_add3_u32 v105, v106, v105, s47
	global_store_short_d16_hi v[148:149], v105, off offset:560

.LBB0_226:
	s_andn2_b64 vcc, exec, s[0:1]
	v_lshl_add_u64 v[100:101], s[14:15], 0, v[146:147]
	s_cbranch_vccnz .LBB0_228
	v_bfe_u32 v97, v189, 16, 1
	v_add3_u32 v97, v189, v97, s47
	v_lshl_add_u64 v[146:147], v[100:101], 0, v[152:153]
	v_lshl_add_u64 v[146:147], v[146:147], 0, v[250:251]
	global_store_short_d16_hi v[146:147], v97, off
	v_bfe_u32 v97, v105, 16, 1
	v_add3_u32 v97, v105, v97, s47
	global_store_short_d16_hi v[146:147], v97, off offset:512
	v_bfe_u32 v97, v133, 16, 1
	v_add3_u32 v97, v133, v97, s47
	global_store_short_d16_hi v[146:147], v97, off offset:16
	v_bfe_u32 v97, v102, 16, 1
	v_add3_u32 v97, v102, v97, s47
	global_store_short_d16_hi v[146:147], v97, off offset:528
	v_bfe_u32 v97, v113, 16, 1
	v_add3_u32 v97, v113, v97, s47
	global_store_short_d16_hi v[146:147], v97, off offset:32
	v_bfe_u32 v97, v99, 16, 1
	v_add3_u32 v97, v99, v97, s47
	global_store_short_d16_hi v[146:147], v97, off offset:544
	v_bfe_u32 v97, v103, 16, 1
	v_add3_u32 v97, v103, v97, s47
	global_store_short_d16_hi v[146:147], v97, off offset:48
	v_bfe_u32 v97, v98, 16, 1
	v_add3_u32 v97, v98, v97, s47
	global_store_short_d16_hi v[146:147], v97, off offset:560

.LBB0_230:
	s_andn2_b64 vcc, exec, s[0:1]
	v_lshl_add_u64 v[92:93], s[14:15], 0, v[142:143]
	s_cbranch_vccnz .LBB0_232
	v_bfe_u32 v89, v133, 16, 1
	v_add3_u32 v89, v133, v89, s47
	v_lshl_add_u64 v[142:143], v[92:93], 0, v[152:153]
	v_lshl_add_u64 v[142:143], v[142:143], 0, v[250:251]
	global_store_short_d16_hi v[142:143], v89, off
	v_bfe_u32 v89, v97, 16, 1
	v_add3_u32 v89, v97, v89, s47
	global_store_short_d16_hi v[142:143], v89, off offset:512
	v_bfe_u32 v89, v113, 16, 1
	v_add3_u32 v89, v113, v89, s47
	global_store_short_d16_hi v[142:143], v89, off offset:16
	v_bfe_u32 v89, v94, 16, 1
	v_add3_u32 v89, v94, v89, s47
	global_store_short_d16_hi v[142:143], v89, off offset:528
	v_bfe_u32 v89, v105, 16, 1
	v_add3_u32 v89, v105, v89, s47
	global_store_short_d16_hi v[142:143], v89, off offset:32
	v_bfe_u32 v89, v91, 16, 1
	v_add3_u32 v89, v91, v89, s47
	global_store_short_d16_hi v[142:143], v89, off offset:544
	v_bfe_u32 v89, v95, 16, 1
	v_add3_u32 v89, v95, v89, s47
	global_store_short_d16_hi v[142:143], v89, off offset:48
	v_bfe_u32 v89, v90, 16, 1
	v_add3_u32 v89, v90, v89, s47
	global_store_short_d16_hi v[142:143], v89, off offset:560

.LBB0_234:
	s_andn2_b64 vcc, exec, s[0:1]
	v_lshl_add_u64 v[84:85], s[14:15], 0, v[140:141]
	s_cbranch_vccnz .LBB0_236
	v_bfe_u32 v81, v113, 16, 1
	v_add3_u32 v81, v113, v81, s47
	v_lshl_add_u64 v[140:141], v[84:85], 0, v[152:153]
	v_lshl_add_u64 v[140:141], v[140:141], 0, v[250:251]
	global_store_short_d16_hi v[140:141], v81, off
	v_bfe_u32 v81, v89, 16, 1
	v_add3_u32 v81, v89, v81, s47
	global_store_short_d16_hi v[140:141], v81, off offset:512
	v_bfe_u32 v81, v105, 16, 1
	v_add3_u32 v81, v105, v81, s47
	global_store_short_d16_hi v[140:141], v81, off offset:16
	v_bfe_u32 v81, v86, 16, 1
	v_add3_u32 v81, v86, v81, s47
	global_store_short_d16_hi v[140:141], v81, off offset:528
	v_bfe_u32 v81, v97, 16, 1
	v_add3_u32 v81, v97, v81, s47
	global_store_short_d16_hi v[140:141], v81, off offset:32
	v_bfe_u32 v81, v83, 16, 1
	v_add3_u32 v81, v83, v81, s47
	global_store_short_d16_hi v[140:141], v81, off offset:544
	v_bfe_u32 v81, v87, 16, 1
	v_add3_u32 v81, v87, v81, s47
	global_store_short_d16_hi v[140:141], v81, off offset:48
	v_bfe_u32 v81, v82, 16, 1
	v_add3_u32 v81, v82, v81, s47
	global_store_short_d16_hi v[140:141], v81, off offset:560

.LBB0_238:
	s_andn2_b64 vcc, exec, s[0:1]
	v_lshl_add_u64 v[76:77], s[14:15], 0, v[138:139]
	s_cbranch_vccnz .LBB0_240
	v_bfe_u32 v73, v105, 16, 1
	v_add3_u32 v73, v105, v73, s47
	v_lshl_add_u64 v[138:139], v[76:77], 0, v[152:153]
	v_lshl_add_u64 v[138:139], v[138:139], 0, v[250:251]
	global_store_short_d16_hi v[138:139], v73, off
	v_bfe_u32 v73, v81, 16, 1
	v_add3_u32 v73, v81, v73, s47
	global_store_short_d16_hi v[138:139], v73, off offset:512
	v_bfe_u32 v73, v97, 16, 1
	v_add3_u32 v73, v97, v73, s47
	global_store_short_d16_hi v[138:139], v73, off offset:16
	v_bfe_u32 v73, v78, 16, 1
	v_add3_u32 v73, v78, v73, s47
	global_store_short_d16_hi v[138:139], v73, off offset:528
	v_bfe_u32 v73, v89, 16, 1
	v_add3_u32 v73, v89, v73, s47
	global_store_short_d16_hi v[138:139], v73, off offset:32
	v_bfe_u32 v73, v75, 16, 1
	v_add3_u32 v73, v75, v73, s47
	global_store_short_d16_hi v[138:139], v73, off offset:544
	v_bfe_u32 v73, v79, 16, 1
	v_add3_u32 v73, v79, v73, s47
	global_store_short_d16_hi v[138:139], v73, off offset:48
	v_bfe_u32 v73, v74, 16, 1
	v_add3_u32 v73, v74, v73, s47
	global_store_short_d16_hi v[138:139], v73, off offset:560

.LBB0_242:
	s_andn2_b64 vcc, exec, s[0:1]
	v_lshl_add_u64 v[66:67], s[14:15], 0, v[134:135]
	s_cbranch_vccnz .LBB0_244
	v_bfe_u32 v65, v97, 16, 1
	v_add3_u32 v65, v97, v65, s47
	v_lshl_add_u64 v[134:135], v[66:67], 0, v[152:153]
	v_lshl_add_u64 v[134:135], v[134:135], 0, v[250:251]
	global_store_short_d16_hi v[134:135], v65, off
	v_bfe_u32 v65, v73, 16, 1
	v_add3_u32 v65, v73, v65, s47
	global_store_short_d16_hi v[134:135], v65, off offset:512
	v_bfe_u32 v65, v89, 16, 1
	v_add3_u32 v65, v89, v65, s47
	global_store_short_d16_hi v[134:135], v65, off offset:16
	v_bfe_u32 v65, v70, 16, 1
	v_add3_u32 v65, v70, v65, s47
	global_store_short_d16_hi v[134:135], v65, off offset:528
	v_bfe_u32 v65, v81, 16, 1
	v_add3_u32 v65, v81, v65, s47
	global_store_short_d16_hi v[134:135], v65, off offset:32
	v_bfe_u32 v65, v69, 16, 1
	v_add3_u32 v65, v69, v65, s47
	global_store_short_d16_hi v[134:135], v65, off offset:544
	v_bfe_u32 v65, v71, 16, 1
	v_add3_u32 v65, v71, v65, s47
	global_store_short_d16_hi v[134:135], v65, off offset:48
	v_bfe_u32 v65, v68, 16, 1
	v_add3_u32 v65, v68, v65, s47
	global_store_short_d16_hi v[134:135], v65, off offset:560

.LBB0_246:
	s_andn2_b64 vcc, exec, s[26:27]
	s_cbranch_vccnz .LBB0_248
	v_bfe_u32 v70, v63, 16, 1
	v_add3_u32 v63, v63, v70, s47
	v_lshl_add_u64 v[70:71], v[124:125], 0, v[152:153]
	v_lshl_add_u64 v[70:71], v[70:71], 0, v[250:251]
	global_store_short_d16_hi v[70:71], v63, off offset:1024
	v_bfe_u32 v63, v60, 16, 1
	v_add3_u32 v60, v60, v63, s47
	global_store_short_d16_hi v[70:71], v60, off offset:1536
	v_bfe_u32 v60, v62, 16, 1
	v_add3_u32 v60, v62, v60, s47
	global_store_short_d16_hi v[70:71], v60, off offset:1040
	v_bfe_u32 v60, v58, 16, 1
	v_add3_u32 v58, v58, v60, s47
	global_store_short_d16_hi v[70:71], v58, off offset:1552
	v_bfe_u32 v58, v61, 16, 1
	v_add3_u32 v58, v61, v58, s47
	global_store_short_d16_hi v[70:71], v58, off offset:1056
	v_bfe_u32 v58, v57, 16, 1
	v_add3_u32 v57, v57, v58, s47
	global_store_short_d16_hi v[70:71], v57, off offset:1568
	v_bfe_u32 v57, v59, 16, 1
	v_add3_u32 v57, v59, v57, s47
	global_store_short_d16_hi v[70:71], v57, off offset:1072
	v_bfe_u32 v57, v56, 16, 1
	v_add3_u32 v56, v56, v57, s47
	global_store_short_d16_hi v[70:71], v56, off offset:1584

.LBB0_250:
	s_andn2_b64 vcc, exec, s[0:1]
	s_cbranch_vccnz .LBB0_252
	v_bfe_u32 v56, v55, 16, 1
	v_add3_u32 v55, v55, v56, s47
	v_lshl_add_u64 v[56:57], v[116:117], 0, v[152:153]
	v_lshl_add_u64 v[56:57], v[56:57], 0, v[250:251]
	global_store_short_d16_hi v[56:57], v55, off offset:1024
	v_bfe_u32 v55, v52, 16, 1
	v_add3_u32 v52, v52, v55, s47
	global_store_short_d16_hi v[56:57], v52, off offset:1536
	v_bfe_u32 v52, v54, 16, 1
	v_add3_u32 v52, v54, v52, s47
	global_store_short_d16_hi v[56:57], v52, off offset:1040
	v_bfe_u32 v52, v50, 16, 1
	v_add3_u32 v50, v50, v52, s47
	global_store_short_d16_hi v[56:57], v50, off offset:1552
	v_bfe_u32 v50, v53, 16, 1
	v_add3_u32 v50, v53, v50, s47
	global_store_short_d16_hi v[56:57], v50, off offset:1056
	v_bfe_u32 v50, v49, 16, 1
	v_add3_u32 v49, v49, v50, s47
	global_store_short_d16_hi v[56:57], v49, off offset:1568
	v_bfe_u32 v49, v51, 16, 1
	v_add3_u32 v49, v51, v49, s47
	global_store_short_d16_hi v[56:57], v49, off offset:1072
	v_bfe_u32 v49, v48, 16, 1
	v_add3_u32 v48, v48, v49, s47
	global_store_short_d16_hi v[56:57], v48, off offset:1584

.LBB0_254:
	s_andn2_b64 vcc, exec, s[0:1]
	s_cbranch_vccnz .LBB0_256
	v_bfe_u32 v48, v47, 16, 1
	v_add3_u32 v47, v47, v48, s47
	v_lshl_add_u64 v[48:49], v[108:109], 0, v[152:153]
	v_lshl_add_u64 v[48:49], v[48:49], 0, v[250:251]
	global_store_short_d16_hi v[48:49], v47, off offset:1024
	v_bfe_u32 v47, v44, 16, 1
	v_add3_u32 v44, v44, v47, s47
	global_store_short_d16_hi v[48:49], v44, off offset:1536
	v_bfe_u32 v44, v46, 16, 1
	v_add3_u32 v44, v46, v44, s47
	global_store_short_d16_hi v[48:49], v44, off offset:1040
	v_bfe_u32 v44, v42, 16, 1
	v_add3_u32 v42, v42, v44, s47
	global_store_short_d16_hi v[48:49], v42, off offset:1552
	v_bfe_u32 v42, v45, 16, 1
	v_add3_u32 v42, v45, v42, s47
	global_store_short_d16_hi v[48:49], v42, off offset:1056
	v_bfe_u32 v42, v41, 16, 1
	v_add3_u32 v41, v41, v42, s47
	global_store_short_d16_hi v[48:49], v41, off offset:1568
	v_bfe_u32 v41, v43, 16, 1
	v_add3_u32 v41, v43, v41, s47
	global_store_short_d16_hi v[48:49], v41, off offset:1072
	v_bfe_u32 v41, v40, 16, 1
	v_add3_u32 v40, v40, v41, s47
	global_store_short_d16_hi v[48:49], v40, off offset:1584

.LBB0_258:
	s_andn2_b64 vcc, exec, s[0:1]
	s_cbranch_vccnz .LBB0_260
	v_bfe_u32 v40, v39, 16, 1
	v_add3_u32 v39, v39, v40, s47
	v_lshl_add_u64 v[40:41], v[100:101], 0, v[152:153]
	v_lshl_add_u64 v[40:41], v[40:41], 0, v[250:251]
	global_store_short_d16_hi v[40:41], v39, off offset:1024
	v_bfe_u32 v39, v36, 16, 1
	v_add3_u32 v36, v36, v39, s47
	global_store_short_d16_hi v[40:41], v36, off offset:1536
	v_bfe_u32 v36, v38, 16, 1
	v_add3_u32 v36, v38, v36, s47
	global_store_short_d16_hi v[40:41], v36, off offset:1040
	v_bfe_u32 v36, v34, 16, 1
	v_add3_u32 v34, v34, v36, s47
	global_store_short_d16_hi v[40:41], v34, off offset:1552
	v_bfe_u32 v34, v37, 16, 1
	v_add3_u32 v34, v37, v34, s47
	global_store_short_d16_hi v[40:41], v34, off offset:1056
	v_bfe_u32 v34, v33, 16, 1
	v_add3_u32 v33, v33, v34, s47
	global_store_short_d16_hi v[40:41], v33, off offset:1568
	v_bfe_u32 v33, v35, 16, 1
	v_add3_u32 v33, v35, v33, s47
	global_store_short_d16_hi v[40:41], v33, off offset:1072
	v_bfe_u32 v33, v32, 16, 1
	v_add3_u32 v32, v32, v33, s47
	global_store_short_d16_hi v[40:41], v32, off offset:1584

.LBB0_262:
	s_andn2_b64 vcc, exec, s[0:1]
	s_cbranch_vccnz .LBB0_264
	v_bfe_u32 v32, v31, 16, 1
	v_add3_u32 v31, v31, v32, s47
	v_lshl_add_u64 v[32:33], v[92:93], 0, v[152:153]
	v_lshl_add_u64 v[32:33], v[32:33], 0, v[250:251]
	global_store_short_d16_hi v[32:33], v31, off offset:1024
	v_bfe_u32 v31, v28, 16, 1
	v_add3_u32 v28, v28, v31, s47
	global_store_short_d16_hi v[32:33], v28, off offset:1536
	v_bfe_u32 v28, v30, 16, 1
	v_add3_u32 v28, v30, v28, s47
	global_store_short_d16_hi v[32:33], v28, off offset:1040
	v_bfe_u32 v28, v26, 16, 1
	v_add3_u32 v26, v26, v28, s47
	global_store_short_d16_hi v[32:33], v26, off offset:1552
	v_bfe_u32 v26, v29, 16, 1
	v_add3_u32 v26, v29, v26, s47
	global_store_short_d16_hi v[32:33], v26, off offset:1056
	v_bfe_u32 v26, v25, 16, 1
	v_add3_u32 v25, v25, v26, s47
	global_store_short_d16_hi v[32:33], v25, off offset:1568
	v_bfe_u32 v25, v27, 16, 1
	v_add3_u32 v25, v27, v25, s47
	global_store_short_d16_hi v[32:33], v25, off offset:1072
	v_bfe_u32 v25, v24, 16, 1
	v_add3_u32 v24, v24, v25, s47
	global_store_short_d16_hi v[32:33], v24, off offset:1584

.LBB0_266:
	s_andn2_b64 vcc, exec, s[0:1]
	s_cbranch_vccnz .LBB0_268
	v_bfe_u32 v24, v23, 16, 1
	v_add3_u32 v23, v23, v24, s47
	v_lshl_add_u64 v[24:25], v[84:85], 0, v[152:153]
	v_lshl_add_u64 v[24:25], v[24:25], 0, v[250:251]
	global_store_short_d16_hi v[24:25], v23, off offset:1024
	v_bfe_u32 v23, v20, 16, 1
	v_add3_u32 v20, v20, v23, s47
	global_store_short_d16_hi v[24:25], v20, off offset:1536
	v_bfe_u32 v20, v22, 16, 1
	v_add3_u32 v20, v22, v20, s47
	global_store_short_d16_hi v[24:25], v20, off offset:1040
	v_bfe_u32 v20, v18, 16, 1
	v_add3_u32 v18, v18, v20, s47
	global_store_short_d16_hi v[24:25], v18, off offset:1552
	v_bfe_u32 v18, v21, 16, 1
	v_add3_u32 v18, v21, v18, s47
	global_store_short_d16_hi v[24:25], v18, off offset:1056
	v_bfe_u32 v18, v17, 16, 1
	v_add3_u32 v17, v17, v18, s47
	global_store_short_d16_hi v[24:25], v17, off offset:1568
	v_bfe_u32 v17, v19, 16, 1
	v_add3_u32 v17, v19, v17, s47
	global_store_short_d16_hi v[24:25], v17, off offset:1072
	v_bfe_u32 v17, v16, 16, 1
	v_add3_u32 v16, v16, v17, s47
	global_store_short_d16_hi v[24:25], v16, off offset:1584

.LBB0_270:
	s_andn2_b64 vcc, exec, s[0:1]
	s_cbranch_vccnz .LBB0_272
	v_bfe_u32 v16, v15, 16, 1
	v_add3_u32 v15, v15, v16, s47
	v_lshl_add_u64 v[16:17], v[76:77], 0, v[152:153]
	v_lshl_add_u64 v[16:17], v[16:17], 0, v[250:251]
	global_store_short_d16_hi v[16:17], v15, off offset:1024
	v_bfe_u32 v15, v12, 16, 1
	v_add3_u32 v12, v12, v15, s47
	global_store_short_d16_hi v[16:17], v12, off offset:1536
	v_bfe_u32 v12, v14, 16, 1
	v_add3_u32 v12, v14, v12, s47
	global_store_short_d16_hi v[16:17], v12, off offset:1040
	v_bfe_u32 v12, v10, 16, 1
	v_add3_u32 v10, v10, v12, s47
	global_store_short_d16_hi v[16:17], v10, off offset:1552
	v_bfe_u32 v10, v13, 16, 1
	v_add3_u32 v10, v13, v10, s47
	global_store_short_d16_hi v[16:17], v10, off offset:1056
	v_bfe_u32 v10, v9, 16, 1
	v_add3_u32 v9, v9, v10, s47
	global_store_short_d16_hi v[16:17], v9, off offset:1568
	v_bfe_u32 v9, v11, 16, 1
	v_add3_u32 v9, v11, v9, s47
	global_store_short_d16_hi v[16:17], v9, off offset:1072
	v_bfe_u32 v9, v8, 16, 1
	v_add3_u32 v8, v8, v9, s47
	global_store_short_d16_hi v[16:17], v8, off offset:1584

.LBB0_274:
	s_andn2_b64 vcc, exec, s[0:1]
	s_cbranch_vccnz .LBB0_205
	v_bfe_u32 v8, v7, 16, 1
	v_add3_u32 v7, v7, v8, s47
	v_lshl_add_u64 v[8:9], v[66:67], 0, v[152:153]
	v_lshl_add_u64 v[8:9], v[8:9], 0, v[250:251]
	global_store_short_d16_hi v[8:9], v7, off offset:1024
	v_bfe_u32 v7, v4, 16, 1
	v_add3_u32 v4, v4, v7, s47
	global_store_short_d16_hi v[8:9], v4, off offset:1536
	v_bfe_u32 v4, v6, 16, 1
	v_add3_u32 v4, v6, v4, s47
	global_store_short_d16_hi v[8:9], v4, off offset:1040
	v_bfe_u32 v4, v2, 16, 1
	v_add3_u32 v2, v2, v4, s47
	global_store_short_d16_hi v[8:9], v2, off offset:1552
	v_bfe_u32 v2, v5, 16, 1
	v_add3_u32 v2, v5, v2, s47
	global_store_short_d16_hi v[8:9], v2, off offset:1056
	v_bfe_u32 v2, v1, 16, 1
	v_add3_u32 v1, v1, v2, s47
	global_store_short_d16_hi v[8:9], v1, off offset:1568
	v_bfe_u32 v1, v3, 16, 1
	v_add3_u32 v1, v3, v1, s47
	global_store_short_d16_hi v[8:9], v1, off offset:1072
	v_bfe_u32 v1, v0, 16, 1
	v_add3_u32 v0, v0, v1, s47
	global_store_short_d16_hi v[8:9], v0, off offset:1584
	s_branch .LBB0_205

.LBB0_330:
	v_mov_b32_e32 v40, v220
	s_add_u32 s0, s72, s4
	v_ashrrev_i32_e32 v24, 2, v40
	v_min_i32_e32 v0, 0x7f, v24
	v_lshlrev_b32_e32 v1, 4, v40
	v_and_b32_e32 v6, 48, v1
	v_ashrrev_i32_e32 v1, 31, v0
	v_add_u32_e32 v26, 64, v24
	v_lshlrev_b64 v[0:1], 9, v[0:1]
	v_ashrrev_i32_e32 v25, 31, v24
	v_min_i32_e32 v2, 0x7f, v26
	s_addc_u32 s1, s73, s5
	v_lshrrev_b32_e32 v0, 4, v24
	v_lshlrev_b32_e32 v0, 13, v0
	v_lshl_or_b32 v0, v6, 4, v0
	v_and_b32_e32 v253, 15, v24
	v_lshl_or_b32 v0, v253, 4, v0
	v_add_u32_e32 v0, 0x1000, v0
	v_mov_b32_e32 v1, 0
	v_lshlrev_b64 v[4:5], 9, v[24:25]
	v_lshl_add_u64 v[0:1], s[0:1], 0, v[0:1]
	v_ashrrev_i32_e32 v3, 31, v2
	v_or_b32_e32 v4, v4, v6
	v_add_co_u32_e32 v0, vcc, s3, v0
	v_lshlrev_b64 v[2:3], 9, v[2:3]
	v_lshl_add_u64 v[4:5], s[0:1], 0, v[4:5]
	v_addc_co_u32_e32 v1, vcc, 0, v1, vcc
	v_lshrrev_b32_e32 v2, 4, v24
	v_lshlrev_b32_e32 v2, 13, v2
	v_lshl_or_b32 v2, v6, 4, v2
	v_and_b32_e32 v253, 15, v24
	v_lshl_or_b32 v2, v253, 4, v2
	v_add_u32_e32 v2, 0x9000, v2
	v_mov_b32_e32 v3, 0
	v_lshl_add_u64 v[6:7], s[0:1], 0, v[2:3]
	v_add_co_u32_e32 v2, vcc, s22, v4
	global_load_dwordx4 v[8:11], v[0:1], off offset:-4096
	s_nop 0
	v_addc_co_u32_e32 v3, vcc, 0, v5, vcc
	v_add_co_u32_e32 v4, vcc, s23, v4
	global_load_dwordx4 v[12:15], v[2:3], off
	s_nop 0
	v_addc_co_u32_e32 v5, vcc, 0, v5, vcc
	v_add_co_u32_e32 v6, vcc, s3, v6
	global_load_dwordx4 v[16:19], v[4:5], off
	s_nop 0
	v_addc_co_u32_e32 v7, vcc, 0, v7, vcc
	global_load_dwordx4 v[20:23], v[6:7], off offset:-4096
	v_lshrrev_b32_e32 v41, 4, v40
	v_sub_u32_e32 v25, 0, v41
	v_xor_b32_e32 v25, v40, v25
	v_lshlrev_b32_e32 v25, 4, v25
	v_and_b32_e32 v25, 48, v25
	v_lshl_or_b32 v148, v24, 6, v25
	v_lshl_or_b32 v149, v26, 6, v25
	global_load_dwordx4 v[24:27], v[2:3], off offset:64
	global_load_dwordx4 v[28:31], v[4:5], off offset:64
	global_load_dwordx4 v[32:35], v[0:1], off offset:-3072
	global_load_dwordx4 v[36:39], v[6:7], off offset:-3072
	v_lshrrev_b32_e32 v42, 2, v40
	v_sub_u32_e32 v42, 0, v42
	v_xor_b32_e32 v41, v41, v42
	v_and_b32_e32 v42, 15, v40
	v_lshrrev_b32_e32 v43, 1, v40
	v_lshlrev_b32_e32 v41, 4, v41
	v_and_or_b32 v42, v43, s24, v42
	v_and_b32_e32 v41, 48, v41
	v_lshlrev_b32_e32 v40, 6, v40
	v_lshl_or_b32 v140, v42, 6, v41
	v_and_or_b32 v144, v40, s25, v41
	s_waitcnt vmcnt(7)
	ds_write_b128 v148, v[8:11]
	s_waitcnt vmcnt(6)
	ds_write_b128 v148, v[12:15] offset:16384
	s_waitcnt vmcnt(5)
	ds_write_b128 v149, v[16:19] offset:16384
	s_waitcnt vmcnt(4)
	ds_write_b128 v149, v[20:23]
	s_waitcnt lgkmcnt(0)
	s_barrier
	global_load_dwordx4 v[8:11], v[0:1], off offset:-2048
	global_load_dwordx4 v[12:15], v[6:7], off offset:-2048
	global_load_dwordx4 v[16:19], v[2:3], off offset:128
	global_load_dwordx4 v[20:23], v[4:5], off offset:128
	ds_read_b128 v[40:43], v140
	ds_read_b128 v[44:47], v140 offset:1024
	ds_read_b128 v[48:51], v144 offset:16384
	ds_read_b128 v[52:55], v144 offset:17408
	ds_read_b128 v[56:59], v140 offset:2048
	ds_read_b128 v[60:63], v140 offset:3072
	ds_read_b128 v[68:71], v144 offset:18432
	ds_read_b128 v[72:75], v144 offset:19456
	s_setprio 1
	s_waitcnt lgkmcnt(5)
	v_mfma_f32_16x16x32_bf16 v[76:79], v[48:51], v[40:43], 0
	s_waitcnt lgkmcnt(4)
	v_mfma_f32_16x16x32_bf16 v[80:83], v[52:55], v[40:43], 0
	s_waitcnt lgkmcnt(1)
	v_mfma_f32_16x16x32_bf16 v[84:87], v[68:71], v[40:43], 0
	s_waitcnt lgkmcnt(0)
	v_mfma_f32_16x16x32_bf16 v[40:43], v[72:75], v[40:43], 0
	v_mfma_f32_16x16x32_bf16 v[88:91], v[48:51], v[44:47], 0
	v_mfma_f32_16x16x32_bf16 v[92:95], v[52:55], v[44:47], 0
	v_mfma_f32_16x16x32_bf16 v[96:99], v[68:71], v[44:47], 0
	v_mfma_f32_16x16x32_bf16 v[44:47], v[72:75], v[44:47], 0
	v_mfma_f32_16x16x32_bf16 v[100:103], v[48:51], v[56:59], 0
	v_mfma_f32_16x16x32_bf16 v[104:107], v[52:55], v[56:59], 0
	v_mfma_f32_16x16x32_bf16 v[108:111], v[68:71], v[56:59], 0
	v_mfma_f32_16x16x32_bf16 v[56:59], v[72:75], v[56:59], 0
	v_mfma_f32_16x16x32_bf16 v[48:51], v[48:51], v[60:63], 0
	v_mfma_f32_16x16x32_bf16 v[52:55], v[52:55], v[60:63], 0
	v_mfma_f32_16x16x32_bf16 v[68:71], v[68:71], v[60:63], 0
	v_mfma_f32_16x16x32_bf16 v[60:63], v[72:75], v[60:63], 0
	s_setprio 0
	s_waitcnt vmcnt(5)
	ds_write_b128 v148, v[32:35] offset:8192
	s_waitcnt vmcnt(4)
	ds_write_b128 v148, v[36:39] offset:12288
	ds_write_b128 v148, v[24:27] offset:24576
	ds_write_b128 v148, v[28:31] offset:28672
	s_waitcnt lgkmcnt(0)
	s_barrier
	global_load_dwordx4 v[24:27], v[0:1], off offset:-1024
	global_load_dwordx4 v[28:31], v[6:7], off offset:-1024
	global_load_dwordx4 v[32:35], v[2:3], off offset:192
	global_load_dwordx4 v[36:39], v[4:5], off offset:192
	ds_read_b128 v[72:75], v140 offset:8192
	ds_read_b128 v[112:115], v144 offset:24576
	ds_read_b128 v[116:119], v140 offset:9216
	ds_read_b128 v[120:123], v144 offset:25600
	ds_read_b128 v[124:127], v140 offset:10240
	ds_read_b128 v[128:131], v144 offset:26624
	ds_read_b128 v[132:135], v140 offset:11264
	ds_read_b128 v[136:139], v144 offset:27648
	s_setprio 1
	s_waitcnt lgkmcnt(6)
	v_mfma_f32_16x16x32_bf16 v[76:79], v[112:115], v[72:75], v[76:79]
	s_waitcnt lgkmcnt(4)
	v_mfma_f32_16x16x32_bf16 v[80:83], v[120:123], v[72:75], v[80:83]
	s_waitcnt lgkmcnt(2)
	v_mfma_f32_16x16x32_bf16 v[84:87], v[128:131], v[72:75], v[84:87]
	s_waitcnt lgkmcnt(0)
	v_mfma_f32_16x16x32_bf16 v[40:43], v[136:139], v[72:75], v[40:43]
	v_mfma_f32_16x16x32_bf16 v[72:75], v[112:115], v[116:119], v[88:91]
	v_mfma_f32_16x16x32_bf16 v[88:91], v[120:123], v[116:119], v[92:95]
	v_mfma_f32_16x16x32_bf16 v[92:95], v[128:131], v[116:119], v[96:99]
	v_mfma_f32_16x16x32_bf16 v[44:47], v[136:139], v[116:119], v[44:47]
	v_mfma_f32_16x16x32_bf16 v[96:99], v[112:115], v[124:127], v[100:103]
	v_mfma_f32_16x16x32_bf16 v[100:103], v[120:123], v[124:127], v[104:107]
	v_mfma_f32_16x16x32_bf16 v[104:107], v[128:131], v[124:127], v[108:111]
	v_mfma_f32_16x16x32_bf16 v[56:59], v[136:139], v[124:127], v[56:59]
	v_mfma_f32_16x16x32_bf16 v[48:51], v[112:115], v[132:135], v[48:51]
	v_mfma_f32_16x16x32_bf16 v[52:55], v[120:123], v[132:135], v[52:55]
	v_mfma_f32_16x16x32_bf16 v[68:71], v[128:131], v[132:135], v[68:71]
	v_mfma_f32_16x16x32_bf16 v[60:63], v[136:139], v[132:135], v[60:63]
	s_setprio 0
	s_waitcnt vmcnt(7)
	ds_write_b128 v148, v[8:11]
	s_waitcnt vmcnt(6)
	ds_write_b128 v149, v[12:15]
	s_waitcnt vmcnt(5)
	ds_write_b128 v148, v[16:19] offset:16384
	s_waitcnt vmcnt(4)
	ds_write_b128 v149, v[20:23] offset:16384
	s_waitcnt lgkmcnt(0)
	s_barrier
	global_load_dwordx4 v[8:11], v[0:1], off
	global_load_dwordx4 v[12:15], v[6:7], off
	global_load_dwordx4 v[16:19], v[2:3], off offset:256
	global_load_dwordx4 v[20:23], v[4:5], off offset:256
	ds_read_b128 v[108:111], v140
	ds_read_b128 v[112:115], v144 offset:16384
	ds_read_b128 v[116:119], v140 offset:1024
	ds_read_b128 v[120:123], v144 offset:17408
	ds_read_b128 v[124:127], v140 offset:2048
	ds_read_b128 v[128:131], v144 offset:18432
	ds_read_b128 v[132:135], v140 offset:3072
	ds_read_b128 v[136:139], v144 offset:19456
	s_setprio 1
	s_waitcnt lgkmcnt(6)
	v_mfma_f32_16x16x32_bf16 v[76:79], v[112:115], v[108:111], v[76:79]
	s_waitcnt lgkmcnt(4)
	v_mfma_f32_16x16x32_bf16 v[80:83], v[120:123], v[108:111], v[80:83]
	s_waitcnt lgkmcnt(2)
	v_mfma_f32_16x16x32_bf16 v[84:87], v[128:131], v[108:111], v[84:87]
	s_waitcnt lgkmcnt(0)
	v_mfma_f32_16x16x32_bf16 v[40:43], v[136:139], v[108:111], v[40:43]
	v_mfma_f32_16x16x32_bf16 v[72:75], v[112:115], v[116:119], v[72:75]
	v_mfma_f32_16x16x32_bf16 v[88:91], v[120:123], v[116:119], v[88:91]
	v_mfma_f32_16x16x32_bf16 v[92:95], v[128:131], v[116:119], v[92:95]
	v_mfma_f32_16x16x32_bf16 v[44:47], v[136:139], v[116:119], v[44:47]
	v_mfma_f32_16x16x32_bf16 v[96:99], v[112:115], v[124:127], v[96:99]
	v_mfma_f32_16x16x32_bf16 v[100:103], v[120:123], v[124:127], v[100:103]
	v_mfma_f32_16x16x32_bf16 v[104:107], v[128:131], v[124:127], v[104:107]
	v_mfma_f32_16x16x32_bf16 v[56:59], v[136:139], v[124:127], v[56:59]
	v_mfma_f32_16x16x32_bf16 v[48:51], v[112:115], v[132:135], v[48:51]
	v_mfma_f32_16x16x32_bf16 v[52:55], v[120:123], v[132:135], v[52:55]
	v_mfma_f32_16x16x32_bf16 v[68:71], v[128:131], v[132:135], v[68:71]
	v_mfma_f32_16x16x32_bf16 v[60:63], v[136:139], v[132:135], v[60:63]
	s_setprio 0
	s_waitcnt vmcnt(7)
	ds_write_b128 v148, v[24:27] offset:8192
	s_waitcnt vmcnt(6)
	ds_write_b128 v148, v[28:31] offset:12288
	s_waitcnt vmcnt(5)
	ds_write_b128 v148, v[32:35] offset:24576
	s_waitcnt vmcnt(4)
	ds_write_b128 v148, v[36:39] offset:28672
	s_waitcnt lgkmcnt(0)
	s_barrier
	global_load_dwordx4 v[24:27], v[0:1], off offset:1024
	global_load_dwordx4 v[28:31], v[6:7], off offset:1024
	global_load_dwordx4 v[32:35], v[2:3], off offset:320
	global_load_dwordx4 v[36:39], v[4:5], off offset:320
	ds_read_b128 v[108:111], v140 offset:8192
	ds_read_b128 v[112:115], v144 offset:24576
	ds_read_b128 v[116:119], v140 offset:9216
	ds_read_b128 v[120:123], v144 offset:25600
	ds_read_b128 v[124:127], v140 offset:10240
	ds_read_b128 v[128:131], v144 offset:26624
	ds_read_b128 v[132:135], v140 offset:11264
	ds_read_b128 v[136:139], v144 offset:27648
	s_setprio 1
	s_waitcnt lgkmcnt(6)
	v_mfma_f32_16x16x32_bf16 v[76:79], v[112:115], v[108:111], v[76:79]
	s_waitcnt lgkmcnt(4)
	v_mfma_f32_16x16x32_bf16 v[80:83], v[120:123], v[108:111], v[80:83]
	s_waitcnt lgkmcnt(2)
	v_mfma_f32_16x16x32_bf16 v[84:87], v[128:131], v[108:111], v[84:87]
	s_waitcnt lgkmcnt(0)
	v_mfma_f32_16x16x32_bf16 v[40:43], v[136:139], v[108:111], v[40:43]
	v_mfma_f32_16x16x32_bf16 v[72:75], v[112:115], v[116:119], v[72:75]
	v_mfma_f32_16x16x32_bf16 v[88:91], v[120:123], v[116:119], v[88:91]
	v_mfma_f32_16x16x32_bf16 v[92:95], v[128:131], v[116:119], v[92:95]
	v_mfma_f32_16x16x32_bf16 v[44:47], v[136:139], v[116:119], v[44:47]
	v_mfma_f32_16x16x32_bf16 v[96:99], v[112:115], v[124:127], v[96:99]
	v_mfma_f32_16x16x32_bf16 v[100:103], v[120:123], v[124:127], v[100:103]
	v_mfma_f32_16x16x32_bf16 v[104:107], v[128:131], v[124:127], v[104:107]
	v_mfma_f32_16x16x32_bf16 v[56:59], v[136:139], v[124:127], v[56:59]
	v_mfma_f32_16x16x32_bf16 v[48:51], v[112:115], v[132:135], v[48:51]
	v_mfma_f32_16x16x32_bf16 v[52:55], v[120:123], v[132:135], v[52:55]
	v_mfma_f32_16x16x32_bf16 v[68:71], v[128:131], v[132:135], v[68:71]
	v_mfma_f32_16x16x32_bf16 v[60:63], v[136:139], v[132:135], v[60:63]
	s_setprio 0
	s_waitcnt vmcnt(7)
	ds_write_b128 v148, v[8:11]
	s_waitcnt vmcnt(6)
	ds_write_b128 v149, v[12:15]
	s_waitcnt vmcnt(5)
	ds_write_b128 v148, v[16:19] offset:16384
	s_waitcnt vmcnt(4)
	ds_write_b128 v149, v[20:23] offset:16384
	s_waitcnt lgkmcnt(0)
	s_barrier
	global_load_dwordx4 v[8:11], v[0:1], off offset:2048
	global_load_dwordx4 v[12:15], v[6:7], off offset:2048
	global_load_dwordx4 v[16:19], v[2:3], off offset:384
	global_load_dwordx4 v[20:23], v[4:5], off offset:384
	ds_read_b128 v[108:111], v140
	ds_read_b128 v[112:115], v144 offset:16384
	ds_read_b128 v[116:119], v140 offset:1024
	ds_read_b128 v[120:123], v144 offset:17408
	ds_read_b128 v[124:127], v140 offset:2048
	ds_read_b128 v[128:131], v144 offset:18432
	ds_read_b128 v[132:135], v140 offset:3072
	ds_read_b128 v[136:139], v144 offset:19456
	s_setprio 1
	s_waitcnt lgkmcnt(6)
	v_mfma_f32_16x16x32_bf16 v[76:79], v[112:115], v[108:111], v[76:79]
	s_waitcnt lgkmcnt(4)
	v_mfma_f32_16x16x32_bf16 v[80:83], v[120:123], v[108:111], v[80:83]
	s_waitcnt lgkmcnt(2)
	v_mfma_f32_16x16x32_bf16 v[84:87], v[128:131], v[108:111], v[84:87]
	s_waitcnt lgkmcnt(0)
	v_mfma_f32_16x16x32_bf16 v[40:43], v[136:139], v[108:111], v[40:43]
	v_mfma_f32_16x16x32_bf16 v[72:75], v[112:115], v[116:119], v[72:75]
	v_mfma_f32_16x16x32_bf16 v[88:91], v[120:123], v[116:119], v[88:91]
	v_mfma_f32_16x16x32_bf16 v[92:95], v[128:131], v[116:119], v[92:95]
	v_mfma_f32_16x16x32_bf16 v[44:47], v[136:139], v[116:119], v[44:47]
	v_mfma_f32_16x16x32_bf16 v[96:99], v[112:115], v[124:127], v[96:99]
	v_mfma_f32_16x16x32_bf16 v[100:103], v[120:123], v[124:127], v[100:103]
	v_mfma_f32_16x16x32_bf16 v[104:107], v[128:131], v[124:127], v[104:107]
	v_mfma_f32_16x16x32_bf16 v[56:59], v[136:139], v[124:127], v[56:59]
	v_mfma_f32_16x16x32_bf16 v[48:51], v[112:115], v[132:135], v[48:51]
	v_mfma_f32_16x16x32_bf16 v[52:55], v[120:123], v[132:135], v[52:55]
	v_mfma_f32_16x16x32_bf16 v[68:71], v[128:131], v[132:135], v[68:71]
	v_mfma_f32_16x16x32_bf16 v[60:63], v[136:139], v[132:135], v[60:63]
	s_setprio 0
	s_waitcnt vmcnt(7)
	ds_write_b128 v148, v[24:27] offset:8192
	s_waitcnt vmcnt(6)
	ds_write_b128 v148, v[28:31] offset:12288
	s_waitcnt vmcnt(5)
	ds_write_b128 v148, v[32:35] offset:24576
	s_waitcnt vmcnt(4)
	ds_write_b128 v148, v[36:39] offset:28672
	s_waitcnt lgkmcnt(0)
	s_barrier
	global_load_dwordx4 v[24:27], v[0:1], off offset:3072
	global_load_dwordx4 v[28:31], v[6:7], off offset:3072
	global_load_dwordx4 v[32:35], v[2:3], off offset:448
	global_load_dwordx4 v[36:39], v[4:5], off offset:448
	ds_read_b128 v[108:111], v140 offset:8192
	ds_read_b128 v[112:115], v144 offset:24576
	ds_read_b128 v[116:119], v140 offset:9216
	ds_read_b128 v[120:123], v144 offset:25600
	ds_read_b128 v[124:127], v140 offset:10240
	ds_read_b128 v[128:131], v144 offset:26624
	ds_read_b128 v[132:135], v140 offset:11264
	ds_read_b128 v[136:139], v144 offset:27648
	s_setprio 1
	s_waitcnt lgkmcnt(6)
	v_mfma_f32_16x16x32_bf16 v[76:79], v[112:115], v[108:111], v[76:79]
	s_waitcnt lgkmcnt(4)
	v_mfma_f32_16x16x32_bf16 v[80:83], v[120:123], v[108:111], v[80:83]
	s_waitcnt lgkmcnt(2)
	v_mfma_f32_16x16x32_bf16 v[84:87], v[128:131], v[108:111], v[84:87]
	s_waitcnt lgkmcnt(0)
	v_mfma_f32_16x16x32_bf16 v[40:43], v[136:139], v[108:111], v[40:43]
	v_mfma_f32_16x16x32_bf16 v[72:75], v[112:115], v[116:119], v[72:75]
	v_mfma_f32_16x16x32_bf16 v[88:91], v[120:123], v[116:119], v[88:91]
	v_mfma_f32_16x16x32_bf16 v[92:95], v[128:131], v[116:119], v[92:95]
	v_mfma_f32_16x16x32_bf16 v[44:47], v[136:139], v[116:119], v[44:47]
	v_mfma_f32_16x16x32_bf16 v[96:99], v[112:115], v[124:127], v[96:99]
	v_mfma_f32_16x16x32_bf16 v[100:103], v[120:123], v[124:127], v[100:103]
	v_mfma_f32_16x16x32_bf16 v[104:107], v[128:131], v[124:127], v[104:107]
	v_mfma_f32_16x16x32_bf16 v[56:59], v[136:139], v[124:127], v[56:59]
	v_mfma_f32_16x16x32_bf16 v[48:51], v[112:115], v[132:135], v[48:51]
	v_mfma_f32_16x16x32_bf16 v[52:55], v[120:123], v[132:135], v[52:55]
	v_mfma_f32_16x16x32_bf16 v[68:71], v[128:131], v[132:135], v[68:71]
	v_mfma_f32_16x16x32_bf16 v[60:63], v[136:139], v[132:135], v[60:63]
	s_setprio 0
	s_waitcnt vmcnt(7)
	ds_write_b128 v148, v[8:11]
	s_waitcnt vmcnt(6)
	ds_write_b128 v149, v[12:15]
	s_waitcnt vmcnt(5)
	ds_write_b128 v148, v[16:19] offset:16384
	s_waitcnt vmcnt(4)
	ds_write_b128 v149, v[20:23] offset:16384
	s_waitcnt lgkmcnt(0)
	s_barrier
	global_load_dwordx4 v[108:111], v[0:1], off offset:3072
	global_load_dwordx4 v[112:115], v[6:7], off offset:3072
	global_load_dwordx4 v[116:119], v[2:3], off offset:448
	global_load_dwordx4 v[120:123], v[4:5], off offset:448
	ds_read_b128 v[0:3], v140
	ds_read_b128 v[4:7], v144 offset:16384
	ds_read_b128 v[8:11], v140 offset:1024
	ds_read_b128 v[12:15], v144 offset:17408
	ds_read_b128 v[16:19], v140 offset:2048
	ds_read_b128 v[20:23], v144 offset:18432
	ds_read_b128 v[124:127], v140 offset:3072
	ds_read_b128 v[128:131], v144 offset:19456
	s_setprio 1
	s_waitcnt lgkmcnt(6)
	v_mfma_f32_16x16x32_bf16 v[76:79], v[4:7], v[0:3], v[76:79]
	s_waitcnt lgkmcnt(4)
	v_mfma_f32_16x16x32_bf16 v[80:83], v[12:15], v[0:3], v[80:83]
	s_waitcnt lgkmcnt(2)
	v_mfma_f32_16x16x32_bf16 v[84:87], v[20:23], v[0:3], v[84:87]
	s_waitcnt lgkmcnt(0)
	v_mfma_f32_16x16x32_bf16 v[0:3], v[128:131], v[0:3], v[40:43]
	v_mfma_f32_16x16x32_bf16 v[40:43], v[4:7], v[8:11], v[72:75]
	v_mfma_f32_16x16x32_bf16 v[72:75], v[12:15], v[8:11], v[88:91]
	v_mfma_f32_16x16x32_bf16 v[88:91], v[20:23], v[8:11], v[92:95]
	v_mfma_f32_16x16x32_bf16 v[8:11], v[128:131], v[8:11], v[44:47]
	v_mfma_f32_16x16x32_bf16 v[92:95], v[4:7], v[16:19], v[96:99]
	v_mfma_f32_16x16x32_bf16 v[96:99], v[12:15], v[16:19], v[100:103]
	v_mfma_f32_16x16x32_bf16 v[100:103], v[20:23], v[16:19], v[104:107]
	v_mfma_f32_16x16x32_bf16 v[16:19], v[128:131], v[16:19], v[56:59]
	v_mfma_f32_16x16x32_bf16 v[4:7], v[4:7], v[124:127], v[48:51]
	v_mfma_f32_16x16x32_bf16 v[104:107], v[12:15], v[124:127], v[52:55]
	v_mfma_f32_16x16x32_bf16 v[68:71], v[20:23], v[124:127], v[68:71]
	v_mfma_f32_16x16x32_bf16 v[60:63], v[128:131], v[124:127], v[60:63]
	s_setprio 0
	s_waitcnt vmcnt(7)
	ds_write_b128 v148, v[24:27] offset:8192
	s_waitcnt vmcnt(6)
	ds_write_b128 v148, v[28:31] offset:12288
	s_waitcnt vmcnt(5)
	ds_write_b128 v148, v[32:35] offset:24576
	s_waitcnt vmcnt(4)
	ds_write_b128 v148, v[36:39] offset:28672
	s_waitcnt lgkmcnt(0)
	s_barrier
	ds_read_b128 v[12:15], v140 offset:8192
	ds_read_b128 v[124:127], v144 offset:24576
	ds_read_b128 v[20:23], v140 offset:9216
	ds_read_b128 v[128:131], v144 offset:25600
	ds_read_b128 v[132:135], v140 offset:10240
	ds_read_b128 v[136:139], v144 offset:26624
	ds_read_b128 v[140:143], v140 offset:11264
	ds_read_b128 v[144:147], v144 offset:27648
	s_setprio 1
	s_waitcnt lgkmcnt(6)
	v_mfma_f32_16x16x32_bf16 v[76:79], v[124:127], v[12:15], v[76:79]
	s_waitcnt lgkmcnt(4)
	v_mfma_f32_16x16x32_bf16 v[56:59], v[128:131], v[12:15], v[80:83]
	s_waitcnt lgkmcnt(2)
	v_mfma_f32_16x16x32_bf16 v[52:55], v[136:139], v[12:15], v[84:87]
	s_waitcnt lgkmcnt(0)
	v_mfma_f32_16x16x32_bf16 v[48:51], v[144:147], v[12:15], v[0:3]
	v_mfma_f32_16x16x32_bf16 v[44:47], v[124:127], v[20:23], v[40:43]
	v_mfma_f32_16x16x32_bf16 v[40:43], v[128:131], v[20:23], v[72:75]
	v_mfma_f32_16x16x32_bf16 v[36:39], v[136:139], v[20:23], v[88:91]
	v_mfma_f32_16x16x32_bf16 v[32:35], v[144:147], v[20:23], v[8:11]
	v_mfma_f32_16x16x32_bf16 v[28:31], v[124:127], v[132:135], v[92:95]
	v_mfma_f32_16x16x32_bf16 v[24:27], v[128:131], v[132:135], v[96:99]
	v_mfma_f32_16x16x32_bf16 v[20:23], v[136:139], v[132:135], v[100:103]
	v_mfma_f32_16x16x32_bf16 v[16:19], v[144:147], v[132:135], v[16:19]
	v_mfma_f32_16x16x32_bf16 v[12:15], v[124:127], v[140:143], v[4:7]
	v_mfma_f32_16x16x32_bf16 v[8:11], v[128:131], v[140:143], v[104:107]
	v_mfma_f32_16x16x32_bf16 v[4:7], v[136:139], v[140:143], v[68:71]
	v_mfma_f32_16x16x32_bf16 v[0:3], v[144:147], v[140:143], v[60:63]
	s_setprio 0
	s_nop 1
	v_mov_b32_e32 v60, v220
	s_waitcnt vmcnt(3)
	ds_write_b128 v148, v[108:111]
	s_waitcnt vmcnt(2)
	ds_write_b128 v149, v[112:115]
	s_waitcnt vmcnt(1)
	ds_write_b128 v148, v[116:119] offset:16384
	s_waitcnt vmcnt(0)
	ds_write_b128 v149, v[120:123] offset:16384
	s_waitcnt lgkmcnt(0)
	s_barrier
	s_bfe_u32 s0, s35, 0x20007
	v_and_b32_e32 v62, 15, v60
	v_and_b32_e32 v61, 64, v60
	v_ashrrev_i32_e32 v63, 1, v60
	v_lshrrev_b32_e32 v60, 2, v60
	v_and_or_b32 v71, v60, 12, v61
	v_cvt_f32_ubyte0_e32 v60, s0
	v_sub_f32_e32 v60, 0xc0a00000, v60
	v_cmp_gt_f32_e32 vcc, s27, v60
	s_and_b64 s[0:1], vcc, exec
	s_cselect_b32 s0, 0xffffffc0, 0
	v_cndmask_b32_e32 v61, 0, v64, vcc
	v_add_f32_e32 v60, v60, v61
	v_exp_f32_e32 v60, v60
	v_and_or_b32 v72, v63, s26, v62
	v_lshlrev_b32_e32 v63, 7, v63
	v_lshlrev_b32_e32 v62, 7, v62
	v_ldexp_f32 v68, v60, s0
	v_sub_f32_e32 v69, 1.0, v68
	v_add_f32_e32 v60, -1.0, v69
	v_sub_f32_e32 v61, v60, v69
	v_add_f32_e32 v61, 1.0, v61
	v_sub_f32_e64 v60, -v68, v60
	v_add_f32_e32 v70, v60, v61
	v_frexp_mant_f32_e32 v60, v69
	v_cmp_gt_f32_e32 vcc, s28, v60
	v_cvt_f64_f32_e32 v[60:61], v69
	v_frexp_exp_i32_f64_e32 v60, v[60:61]
	v_subbrev_co_u32_e32 v60, vcc, 0, v60, vcc
	v_sub_u32_e32 v61, 0, v60
	v_ldexp_f32 v69, v69, v61
	v_ldexp_f32 v61, v70, v61
	v_add_f32_e32 v70, -1.0, v69
	v_add_f32_e32 v73, 1.0, v70
	v_sub_f32_e32 v73, v69, v73
	v_add_f32_e32 v73, v61, v73
	v_add_f32_e32 v74, v70, v73
	v_sub_f32_e32 v70, v74, v70
	v_sub_f32_e32 v70, v73, v70
	v_add_f32_e32 v73, 1.0, v69
	v_add_f32_e32 v75, -1.0, v73
	v_sub_f32_e32 v69, v69, v75
	v_add_f32_e32 v61, v61, v69
	v_add_f32_e32 v69, v73, v61
	v_sub_f32_e32 v73, v69, v73
	v_sub_f32_e32 v61, v61, v73
	v_rcp_f32_e32 v73, v69
	v_cvt_f32_i32_e32 v60, v60
	v_cmp_nlt_f32_e32 vcc, 1.0, v68
	v_cmp_gt_i32_e64 s[0:1], v72, v71
	v_mul_f32_e32 v75, v74, v73
	v_mul_f32_e32 v80, v69, v75
	v_fma_f32 v81, v75, v69, -v80
	v_fmac_f32_e32 v81, v75, v61
	v_add_f32_e32 v82, v80, v81
	v_sub_f32_e32 v83, v74, v82
	v_sub_f32_e32 v74, v74, v83
	v_sub_f32_e32 v80, v82, v80
	v_sub_f32_e32 v74, v74, v82
	v_add_f32_e32 v70, v70, v74
	v_sub_f32_e32 v74, v80, v81
	v_add_f32_e32 v70, v74, v70
	v_add_f32_e32 v74, v83, v70
	v_mul_f32_e32 v80, v73, v74
	v_mul_f32_e32 v81, v69, v80
	v_fma_f32 v69, v80, v69, -v81
	v_fmac_f32_e32 v69, v80, v61
	v_sub_f32_e32 v61, v83, v74
	v_add_f32_e32 v61, v70, v61
	v_add_f32_e32 v70, v81, v69
	v_sub_f32_e32 v82, v74, v70
	v_sub_f32_e32 v74, v74, v82
	v_sub_f32_e32 v81, v70, v81
	v_sub_f32_e32 v70, v74, v70
	v_add_f32_e32 v61, v61, v70
	v_sub_f32_e32 v69, v81, v69
	v_add_f32_e32 v61, v69, v61
	v_add_f32_e32 v69, v75, v80
	v_add_f32_e32 v61, v82, v61
	v_sub_f32_e32 v70, v69, v75
	v_mul_f32_e32 v61, v73, v61
	v_sub_f32_e32 v70, v80, v70
	v_add_f32_e32 v61, v70, v61
	v_mul_f32_e32 v75, 0x3f317218, v60
	v_add_f32_e32 v70, v69, v61
	v_fma_f32 v80, v60, s29, -v75
	v_mul_f32_e32 v73, v70, v70
	v_fmac_f32_e32 v80, 0xb102e308, v60
	v_sub_f32_e32 v60, v70, v69
	v_fmamk_f32 v74, v73, 0x3e9b6dac, v65
	v_sub_f32_e32 v60, v61, v60
	v_add_f32_e32 v61, v75, v80
	v_fmaak_f32 v74, v73, v74, 0x3f2aaada
	v_sub_f32_e32 v69, v61, v75
	v_ldexp_f32 v75, v70, 1
	v_mul_f32_e32 v70, v70, v73
	v_mul_f32_e32 v70, v70, v74
	v_add_f32_e32 v73, v75, v70
	v_sub_f32_e32 v74, v73, v75
	v_ldexp_f32 v60, v60, 1
	v_sub_f32_e32 v70, v70, v74
	v_add_f32_e32 v60, v60, v70
	v_add_f32_e32 v70, v73, v60
	v_sub_f32_e32 v73, v70, v73
	v_sub_f32_e32 v60, v60, v73
	v_add_f32_e32 v73, v61, v70
	v_sub_f32_e32 v74, v73, v61
	v_sub_f32_e32 v75, v73, v74
	v_sub_f32_e32 v69, v80, v69
	v_sub_f32_e32 v61, v61, v75
	v_sub_f32_e32 v70, v70, v74
	v_add_f32_e32 v61, v70, v61
	v_add_f32_e32 v70, v69, v60
	v_sub_f32_e32 v74, v70, v69
	v_sub_f32_e32 v75, v70, v74
	v_sub_f32_e32 v69, v69, v75
	v_sub_f32_e32 v60, v60, v74
	v_add_f32_e32 v61, v70, v61
	v_add_f32_e32 v60, v60, v69
	v_add_f32_e32 v69, v73, v61
	v_sub_f32_e32 v70, v69, v73
	v_sub_f32_e32 v61, v61, v70
	v_add_f32_e32 v60, v60, v61
	v_add_f32_e32 v60, v69, v60
	v_cndmask_b32_e32 v60, v66, v60, vcc
	v_cmp_neq_f32_e32 vcc, 1.0, v68
	v_or_b32_e32 v75, 1, v71
	v_sub_u32_e32 v61, v72, v75
	v_cndmask_b32_e32 v60, v67, v60, vcc
	v_cmp_gt_f32_e32 vcc, s30, v68
	v_or_b32_e32 v73, 2, v71
	v_cvt_f32_i32_e32 v61, v61
	v_cndmask_b32_e64 v68, v60, -v68, vcc
	v_sub_u32_e32 v60, v72, v71
	v_cvt_f32_i32_e32 v60, v60
	v_sub_u32_e32 v70, v72, v73
	v_or_b32_e32 v74, 3, v71
	v_cvt_f32_i32_e32 v70, v70
	v_mul_f32_e32 v60, v68, v60
	v_mul_f32_e32 v60, 0x3fb8aa3b, v60
	v_exp_f32_e32 v69, v60
	v_mul_f32_e32 v61, v68, v61
	v_mul_f32_e32 v61, 0x3fb8aa3b, v61
	v_mul_f32_e32 v70, v68, v70
	v_mul_f32_e32 v60, v76, v69
	v_sub_u32_e32 v76, v72, v74
	v_cvt_f32_i32_e32 v76, v76
	v_exp_f32_e32 v61, v61
	v_mul_f32_e32 v70, 0x3fb8aa3b, v70
	v_exp_f32_e32 v70, v70
	v_mul_f32_e32 v76, v68, v76
	v_mul_f32_e32 v76, 0x3fb8aa3b, v76
	v_exp_f32_e32 v76, v76
	v_mul_f32_e32 v61, v77, v61
	v_cndmask_b32_e64 v61, 0, v61, s[0:1]
	v_mul_f32_e32 v70, v78, v70
	v_cmp_ge_i32_e64 s[0:1], v72, v73
	v_cmp_lt_i32_e32 vcc, v72, v71
	v_mul_f32_e32 v76, v79, v76
	v_cndmask_b32_e64 v70, 0, v70, s[0:1]
	v_cmp_ge_i32_e64 s[0:1], v72, v74
	v_and_b32_e32 v62, s31, v63
	v_cndmask_b32_e64 v60, v60, 0, vcc
	v_cndmask_b32_e64 v76, 0, v76, s[0:1]
	v_ashrrev_i32_e32 v63, 31, v62
	v_cvt_pk_bf16_f32 v60, v60, v61
	v_cvt_pk_bf16_f32 v61, v70, v76
	v_lshlrev_b64 v[62:63], 1, v[62:63]
	v_and_b32_e32 v76, 64, v71
	v_lshlrev_b32_e32 v76, 5, v76
	v_and_b32_e32 v253, 8, v71
	v_lshl_or_b32 v76, v253, 5, v76
	v_and_b32_e32 v253, 4, v71
	v_lshl_or_b32 v76, v253, 1, v76
	v_and_b32_e32 v253, 15, v72
	v_lshl_or_b32 v76, v253, 4, v76
	s_add_u32 s20, s72, s14
	v_or_b32_e32 v62, v62, v76
	s_addc_u32 s21, s73, s15
	v_lshl_add_u64 v[62:63], s[20:21], 0, v[62:63]
	v_add_co_u32_e64 v62, s[0:1], s34, v62
	v_or_b32_e32 v70, 16, v71
	s_nop 0
	v_addc_co_u32_e64 v63, s[0:1], 0, v63, s[0:1]
	global_store_dwordx2 v[62:63], v[60:61], off
	v_sub_u32_e32 v60, v72, v70
	v_cvt_f32_i32_e32 v60, v60
	v_or_b32_e32 v61, 17, v71
	v_cmp_ge_i32_e64 s[0:1], v72, v70
	v_mul_f32_e32 v40, v40, v69
	v_mul_f32_e32 v60, v68, v60
	v_mul_f32_e32 v60, 0x3fb8aa3b, v60
	v_exp_f32_e32 v60, v60
	v_cndmask_b32_e64 v40, v40, 0, vcc
	v_mul_f32_e32 v20, v20, v69
	v_cndmask_b32_e64 v20, v20, 0, vcc
	v_mul_f32_e32 v56, v56, v60
	v_sub_u32_e32 v60, v72, v61
	v_cvt_f32_i32_e32 v60, v60
	v_cndmask_b32_e64 v56, 0, v56, s[0:1]
	v_cmp_ge_i32_e64 s[0:1], v72, v61
	s_add_i32 s35, s35, s74
	v_mul_f32_e32 v60, v68, v60
	v_mul_f32_e32 v60, 0x3fb8aa3b, v60
	v_exp_f32_e32 v60, v60
	s_add_u32 s4, s4, s8
	v_mul_f32_e32 v0, v0, v69
	s_addc_u32 s5, s5, s9
	v_mul_f32_e32 v57, v57, v60
	v_or_b32_e32 v60, 18, v71
	v_sub_u32_e32 v77, v72, v60
	v_cvt_f32_i32_e32 v77, v77
	v_cndmask_b32_e64 v57, 0, v57, s[0:1]
	v_cmp_ge_i32_e64 s[0:1], v72, v60
	v_cvt_pk_bf16_f32 v56, v56, v57
	v_mul_f32_e32 v77, v68, v77
	v_mul_f32_e32 v77, 0x3fb8aa3b, v77
	v_exp_f32_e32 v77, v77
	v_cndmask_b32_e64 v0, v0, 0, vcc
	s_add_u32 s14, s14, s16
	s_addc_u32 s15, s15, s17
	v_mul_f32_e32 v58, v58, v77
	v_cndmask_b32_e64 v77, 0, v58, s[0:1]
	v_or_b32_e32 v58, 19, v71
	v_sub_u32_e32 v78, v72, v58
	v_cvt_f32_i32_e32 v78, v78
	v_cmp_ge_i32_e64 s[0:1], v72, v58
	s_cmpk_lt_i32 s35, 0x400
	v_mul_f32_e32 v78, v68, v78
	v_mul_f32_e32 v78, 0x3fb8aa3b, v78
	v_exp_f32_e32 v78, v78
	s_nop 0
	v_mul_f32_e32 v59, v59, v78
	v_cndmask_b32_e64 v59, 0, v59, s[0:1]
	v_cvt_pk_bf16_f32 v57, v77, v59
	global_store_dwordx2 v[62:63], v[56:57], off offset:512
	v_or_b32_e32 v57, 32, v71
	v_sub_u32_e32 v56, v72, v57
	v_cvt_f32_i32_e32 v56, v56
	v_cmp_ge_i32_e64 s[0:1], v72, v57
	v_mul_f32_e32 v56, v68, v56
	v_mul_f32_e32 v56, 0x3fb8aa3b, v56
	v_exp_f32_e32 v56, v56
	s_nop 0
	v_mul_f32_e32 v52, v52, v56
	v_or_b32_e32 v56, 33, v71
	v_cndmask_b32_e64 v59, 0, v52, s[0:1]
	v_sub_u32_e32 v52, v72, v56
	v_cvt_f32_i32_e32 v52, v52
	v_cmp_ge_i32_e64 s[0:1], v72, v56
	v_mul_f32_e32 v52, v68, v52
	v_mul_f32_e32 v52, 0x3fb8aa3b, v52
	v_exp_f32_e32 v52, v52
	s_nop 0
	v_mul_f32_e32 v52, v53, v52
	v_or_b32_e32 v53, 34, v71
	v_cndmask_b32_e64 v77, 0, v52, s[0:1]
	v_sub_u32_e32 v52, v72, v53
	v_cvt_f32_i32_e32 v52, v52
	v_cmp_ge_i32_e64 s[0:1], v72, v53
	v_mul_f32_e32 v52, v68, v52
	v_mul_f32_e32 v52, 0x3fb8aa3b, v52
	v_exp_f32_e32 v52, v52
	s_nop 0
	v_mul_f32_e32 v52, v54, v52
	v_cndmask_b32_e64 v78, 0, v52, s[0:1]
	v_or_b32_e32 v52, 35, v71
	v_sub_u32_e32 v54, v72, v52
	v_cvt_f32_i32_e32 v54, v54
	v_cmp_ge_i32_e64 s[0:1], v72, v52
	v_mul_f32_e32 v54, v68, v54
	v_mul_f32_e32 v54, 0x3fb8aa3b, v54
	v_exp_f32_e32 v54, v54
	s_nop 0
	v_mul_f32_e32 v54, v55, v54
	v_cndmask_b32_e64 v55, 0, v54, s[0:1]
	v_cvt_pk_bf16_f32 v55, v78, v55
	v_cvt_pk_bf16_f32 v54, v59, v77
	global_store_dwordx2 v[62:63], v[54:55], off offset:1024
	v_or_b32_e32 v55, 48, v71
	v_sub_u32_e32 v54, v72, v55
	v_cvt_f32_i32_e32 v54, v54
	v_cmp_ge_i32_e64 s[0:1], v72, v55
	v_mul_f32_e32 v54, v68, v54
	v_mul_f32_e32 v54, 0x3fb8aa3b, v54
	v_exp_f32_e32 v54, v54
	s_nop 0
	v_mul_f32_e32 v48, v48, v54
	v_or_b32_e32 v54, 49, v71
	v_cndmask_b32_e64 v59, 0, v48, s[0:1]
	v_sub_u32_e32 v48, v72, v54
	v_cvt_f32_i32_e32 v48, v48
	v_cmp_ge_i32_e64 s[0:1], v72, v54
	v_mul_f32_e32 v48, v68, v48
	v_mul_f32_e32 v48, 0x3fb8aa3b, v48
	v_exp_f32_e32 v48, v48
	s_nop 0
	v_mul_f32_e32 v48, v49, v48
	v_or_b32_e32 v49, 50, v71
	v_cndmask_b32_e64 v77, 0, v48, s[0:1]
	v_sub_u32_e32 v48, v72, v49
	v_cvt_f32_i32_e32 v48, v48
	v_cmp_ge_i32_e64 s[0:1], v72, v49
	v_mul_f32_e32 v48, v68, v48
	v_mul_f32_e32 v48, 0x3fb8aa3b, v48
	v_exp_f32_e32 v48, v48
	s_nop 0
	v_mul_f32_e32 v48, v50, v48
	v_cndmask_b32_e64 v78, 0, v48, s[0:1]
	v_or_b32_e32 v48, 51, v71
	v_sub_u32_e32 v50, v72, v48
	v_cvt_f32_i32_e32 v50, v50
	v_cmp_ge_i32_e64 s[0:1], v72, v48
	v_mul_f32_e32 v50, v68, v50
	v_mul_f32_e32 v50, 0x3fb8aa3b, v50
	v_exp_f32_e32 v50, v50
	s_nop 0
	v_mul_f32_e32 v50, v51, v50
	v_cndmask_b32_e64 v51, 0, v50, s[0:1]
	v_cvt_pk_bf16_f32 v50, v59, v77
	v_cvt_pk_bf16_f32 v51, v78, v51
	global_store_dwordx2 v[62:63], v[50:51], off offset:1536
	v_or_b32_e32 v50, 16, v72
	v_sub_u32_e32 v51, v50, v71
	v_cvt_f32_i32_e32 v51, v51
	v_cmp_ge_i32_e64 s[0:1], v50, v71
	v_mul_f32_e32 v51, v68, v51
	v_mul_f32_e32 v51, 0x3fb8aa3b, v51
	v_exp_f32_e32 v51, v51
	s_nop 0
	v_mul_f32_e32 v44, v44, v51
	v_sub_u32_e32 v51, v50, v75
	v_cvt_f32_i32_e32 v51, v51
	v_cndmask_b32_e64 v44, 0, v44, s[0:1]
	v_cmp_gt_i32_e64 s[0:1], v50, v71
	v_mul_f32_e32 v51, v68, v51
	v_mul_f32_e32 v51, 0x3fb8aa3b, v51
	v_exp_f32_e32 v51, v51
	s_nop 0
	v_mul_f32_e32 v45, v45, v51
	v_sub_u32_e32 v51, v50, v73
	v_cvt_f32_i32_e32 v51, v51
	v_cndmask_b32_e64 v45, 0, v45, s[0:1]
	v_cmp_ge_i32_e64 s[0:1], v50, v73
	v_cvt_pk_bf16_f32 v44, v44, v45
	v_mul_f32_e32 v51, v68, v51
	v_mul_f32_e32 v51, 0x3fb8aa3b, v51
	v_exp_f32_e32 v51, v51
	s_nop 0
	v_mul_f32_e32 v46, v46, v51
	v_sub_u32_e32 v51, v50, v74
	v_cvt_f32_i32_e32 v51, v51
	v_cndmask_b32_e64 v46, 0, v46, s[0:1]
	v_cmp_ge_i32_e64 s[0:1], v50, v74
	v_mul_f32_e32 v51, v68, v51
	v_mul_f32_e32 v51, 0x3fb8aa3b, v51
	v_exp_f32_e32 v51, v51
	s_nop 0
	v_mul_f32_e32 v47, v47, v51
	v_cndmask_b32_e64 v47, 0, v47, s[0:1]
	v_cvt_pk_bf16_f32 v45, v46, v47
	v_lshlrev_b32_e32 v46, 7, v50
	v_and_b32_e32 v46, 0xfffff87f, v46
	v_ashrrev_i32_e32 v47, 31, v46
	v_lshlrev_b64 v[46:47], 1, v[46:47]
	v_or_b32_e32 v46, v46, v76
	v_lshl_add_u64 v[46:47], s[20:21], 0, v[46:47]
	v_add_co_u32_e64 v46, s[0:1], s34, v46
	s_nop 1
	v_addc_co_u32_e64 v47, s[0:1], 0, v47, s[0:1]
	global_store_dwordx2 v[46:47], v[44:45], off
	v_sub_u32_e32 v44, v50, v61
	v_cvt_f32_i32_e32 v44, v44
	v_cmp_ge_i32_e64 s[0:1], v50, v61
	v_mul_f32_e32 v44, v68, v44
	v_mul_f32_e32 v44, 0x3fb8aa3b, v44
	v_exp_f32_e32 v44, v44
	s_nop 0
	v_mul_f32_e32 v41, v41, v44
	v_sub_u32_e32 v44, v50, v60
	v_cvt_f32_i32_e32 v44, v44
	v_cndmask_b32_e64 v41, 0, v41, s[0:1]
	v_cmp_ge_i32_e64 s[0:1], v50, v60
	v_cvt_pk_bf16_f32 v40, v40, v41
	v_mul_f32_e32 v44, v68, v44
	v_mul_f32_e32 v44, 0x3fb8aa3b, v44
	v_exp_f32_e32 v44, v44
	s_nop 0
	v_mul_f32_e32 v42, v42, v44
	v_sub_u32_e32 v44, v50, v58
	v_cvt_f32_i32_e32 v44, v44
	v_cndmask_b32_e64 v42, 0, v42, s[0:1]
	v_cmp_ge_i32_e64 s[0:1], v50, v58
	v_mul_f32_e32 v44, v68, v44
	v_mul_f32_e32 v44, 0x3fb8aa3b, v44
	v_exp_f32_e32 v44, v44
	s_nop 0
	v_mul_f32_e32 v43, v43, v44
	v_cndmask_b32_e64 v43, 0, v43, s[0:1]
	v_cvt_pk_bf16_f32 v41, v42, v43
	global_store_dwordx2 v[46:47], v[40:41], off offset:512
	v_sub_u32_e32 v40, v50, v57
	v_cvt_f32_i32_e32 v40, v40
	v_cmp_ge_i32_e64 s[0:1], v50, v57
	v_mul_f32_e32 v40, v68, v40
	v_mul_f32_e32 v40, 0x3fb8aa3b, v40
	v_exp_f32_e32 v40, v40
	s_nop 0
	v_mul_f32_e32 v36, v36, v40
	v_sub_u32_e32 v40, v50, v56
	v_cvt_f32_i32_e32 v40, v40
	v_cndmask_b32_e64 v36, 0, v36, s[0:1]
	v_cmp_ge_i32_e64 s[0:1], v50, v56
	v_mul_f32_e32 v40, v68, v40
	v_mul_f32_e32 v40, 0x3fb8aa3b, v40
	v_exp_f32_e32 v40, v40
	s_nop 0
	v_mul_f32_e32 v37, v37, v40
	v_sub_u32_e32 v40, v50, v53
	v_cvt_f32_i32_e32 v40, v40
	v_cndmask_b32_e64 v37, 0, v37, s[0:1]
	v_cmp_ge_i32_e64 s[0:1], v50, v53
	v_cvt_pk_bf16_f32 v36, v36, v37
	v_mul_f32_e32 v40, v68, v40
	v_mul_f32_e32 v40, 0x3fb8aa3b, v40
	v_exp_f32_e32 v40, v40
	s_nop 0
	v_mul_f32_e32 v38, v38, v40
	v_sub_u32_e32 v40, v50, v52
	v_cvt_f32_i32_e32 v40, v40
	v_cndmask_b32_e64 v38, 0, v38, s[0:1]
	v_cmp_ge_i32_e64 s[0:1], v50, v52
	v_mul_f32_e32 v40, v68, v40
	v_mul_f32_e32 v40, 0x3fb8aa3b, v40
	v_exp_f32_e32 v40, v40
	s_nop 0
	v_mul_f32_e32 v39, v39, v40
	v_cndmask_b32_e64 v39, 0, v39, s[0:1]
	v_cvt_pk_bf16_f32 v37, v38, v39
	global_store_dwordx2 v[46:47], v[36:37], off offset:1024
	v_sub_u32_e32 v36, v50, v55
	v_cvt_f32_i32_e32 v36, v36
	v_cmp_ge_i32_e64 s[0:1], v50, v55
	v_mul_f32_e32 v36, v68, v36
	v_mul_f32_e32 v36, 0x3fb8aa3b, v36
	v_exp_f32_e32 v36, v36
	s_nop 0
	v_mul_f32_e32 v32, v32, v36
	v_sub_u32_e32 v36, v50, v54
	v_cvt_f32_i32_e32 v36, v36
	v_cndmask_b32_e64 v32, 0, v32, s[0:1]
	v_cmp_ge_i32_e64 s[0:1], v50, v54
	v_mul_f32_e32 v36, v68, v36
	v_mul_f32_e32 v36, 0x3fb8aa3b, v36
	v_exp_f32_e32 v36, v36
	s_nop 0
	v_mul_f32_e32 v33, v33, v36
	v_sub_u32_e32 v36, v50, v49
	v_cvt_f32_i32_e32 v36, v36
	v_cndmask_b32_e64 v33, 0, v33, s[0:1]
	v_cmp_ge_i32_e64 s[0:1], v50, v49
	v_cvt_pk_bf16_f32 v32, v32, v33
	v_mul_f32_e32 v36, v68, v36
	v_mul_f32_e32 v36, 0x3fb8aa3b, v36
	v_exp_f32_e32 v36, v36
	s_nop 0
	v_mul_f32_e32 v34, v34, v36
	v_sub_u32_e32 v36, v50, v48
	v_cvt_f32_i32_e32 v36, v36
	v_cndmask_b32_e64 v34, 0, v34, s[0:1]
	v_cmp_ge_i32_e64 s[0:1], v50, v48
	v_mul_f32_e32 v36, v68, v36
	v_mul_f32_e32 v36, 0x3fb8aa3b, v36
	v_exp_f32_e32 v36, v36
	s_nop 0
	v_mul_f32_e32 v35, v35, v36
	v_cndmask_b32_e64 v35, 0, v35, s[0:1]
	v_cvt_pk_bf16_f32 v33, v34, v35
	global_store_dwordx2 v[46:47], v[32:33], off offset:1536
	v_or_b32_e32 v32, 32, v72
	v_sub_u32_e32 v33, v32, v71
	v_cvt_f32_i32_e32 v33, v33
	v_cmp_ge_i32_e64 s[0:1], v32, v71
	v_mul_f32_e32 v33, v68, v33
	v_mul_f32_e32 v33, 0x3fb8aa3b, v33
	v_exp_f32_e32 v33, v33
	s_nop 0
	v_mul_f32_e32 v28, v28, v33
	v_sub_u32_e32 v33, v32, v75
	v_cvt_f32_i32_e32 v33, v33
	v_cndmask_b32_e64 v28, 0, v28, s[0:1]
	v_cmp_gt_i32_e64 s[0:1], v32, v71
	v_mul_f32_e32 v33, v68, v33
	v_mul_f32_e32 v33, 0x3fb8aa3b, v33
	v_exp_f32_e32 v33, v33
	s_nop 0
	v_mul_f32_e32 v29, v29, v33
	v_sub_u32_e32 v33, v32, v73
	v_cvt_f32_i32_e32 v33, v33
	v_cndmask_b32_e64 v29, 0, v29, s[0:1]
	v_cmp_ge_i32_e64 s[0:1], v32, v73
	v_cvt_pk_bf16_f32 v28, v28, v29
	v_mul_f32_e32 v33, v68, v33
	v_mul_f32_e32 v33, 0x3fb8aa3b, v33
	v_exp_f32_e32 v33, v33
	s_nop 0
	v_mul_f32_e32 v30, v30, v33
	v_sub_u32_e32 v33, v32, v74
	v_cvt_f32_i32_e32 v33, v33
	v_cndmask_b32_e64 v30, 0, v30, s[0:1]
	v_cmp_ge_i32_e64 s[0:1], v32, v74
	v_mul_f32_e32 v33, v68, v33
	v_mul_f32_e32 v33, 0x3fb8aa3b, v33
	v_exp_f32_e32 v33, v33
	s_nop 0
	v_mul_f32_e32 v31, v31, v33
	v_cndmask_b32_e64 v31, 0, v31, s[0:1]
	v_cvt_pk_bf16_f32 v29, v30, v31
	v_lshlrev_b32_e32 v30, 7, v32
	v_and_b32_e32 v30, 0xfffff87f, v30
	v_ashrrev_i32_e32 v31, 31, v30
	v_lshlrev_b64 v[30:31], 1, v[30:31]
	v_or_b32_e32 v30, v30, v76
	v_lshl_add_u64 v[30:31], s[20:21], 0, v[30:31]
	v_add_co_u32_e64 v30, s[0:1], s34, v30
	s_nop 1
	v_addc_co_u32_e64 v31, s[0:1], 0, v31, s[0:1]
	global_store_dwordx2 v[30:31], v[28:29], off
	v_sub_u32_e32 v28, v32, v70
	v_cvt_f32_i32_e32 v28, v28
	v_cmp_ge_i32_e64 s[0:1], v32, v70
	v_mul_f32_e32 v28, v68, v28
	v_mul_f32_e32 v28, 0x3fb8aa3b, v28
	v_exp_f32_e32 v28, v28
	s_nop 0
	v_mul_f32_e32 v24, v24, v28
	v_sub_u32_e32 v28, v32, v61
	v_cvt_f32_i32_e32 v28, v28
	v_cndmask_b32_e64 v24, 0, v24, s[0:1]
	v_cmp_ge_i32_e64 s[0:1], v32, v61
	v_mul_f32_e32 v28, v68, v28
	v_mul_f32_e32 v28, 0x3fb8aa3b, v28
	v_exp_f32_e32 v28, v28
	s_nop 0
	v_mul_f32_e32 v25, v25, v28
	v_sub_u32_e32 v28, v32, v60
	v_cvt_f32_i32_e32 v28, v28
	v_cndmask_b32_e64 v25, 0, v25, s[0:1]
	v_cmp_ge_i32_e64 s[0:1], v32, v60
	v_cvt_pk_bf16_f32 v24, v24, v25
	v_mul_f32_e32 v28, v68, v28
	v_mul_f32_e32 v28, 0x3fb8aa3b, v28
	v_exp_f32_e32 v28, v28
	s_nop 0
	v_mul_f32_e32 v26, v26, v28
	v_sub_u32_e32 v28, v32, v58
	v_cvt_f32_i32_e32 v28, v28
	v_cndmask_b32_e64 v26, 0, v26, s[0:1]
	v_cmp_ge_i32_e64 s[0:1], v32, v58
	v_mul_f32_e32 v28, v68, v28
	v_mul_f32_e32 v28, 0x3fb8aa3b, v28
	v_exp_f32_e32 v28, v28
	s_nop 0
	v_mul_f32_e32 v27, v27, v28
	v_cndmask_b32_e64 v27, 0, v27, s[0:1]
	v_cvt_pk_bf16_f32 v25, v26, v27
	global_store_dwordx2 v[30:31], v[24:25], off offset:512
	v_sub_u32_e32 v24, v32, v56
	v_cvt_f32_i32_e32 v24, v24
	v_cmp_ge_i32_e64 s[0:1], v32, v56
	v_mul_f32_e32 v24, v68, v24
	v_mul_f32_e32 v24, 0x3fb8aa3b, v24
	v_exp_f32_e32 v24, v24
	s_nop 0
	v_mul_f32_e32 v21, v21, v24
	v_sub_u32_e32 v24, v32, v53
	v_cvt_f32_i32_e32 v24, v24
	v_cndmask_b32_e64 v21, 0, v21, s[0:1]
	v_cmp_ge_i32_e64 s[0:1], v32, v53
	v_cvt_pk_bf16_f32 v20, v20, v21
	v_mul_f32_e32 v24, v68, v24
	v_mul_f32_e32 v24, 0x3fb8aa3b, v24
	v_exp_f32_e32 v24, v24
	s_nop 0
	v_mul_f32_e32 v22, v22, v24
	v_sub_u32_e32 v24, v32, v52
	v_cvt_f32_i32_e32 v24, v24
	v_cndmask_b32_e64 v22, 0, v22, s[0:1]
	v_cmp_ge_i32_e64 s[0:1], v32, v52
	v_mul_f32_e32 v24, v68, v24
	v_mul_f32_e32 v24, 0x3fb8aa3b, v24
	v_exp_f32_e32 v24, v24
	s_nop 0
	v_mul_f32_e32 v23, v23, v24
	v_cndmask_b32_e64 v23, 0, v23, s[0:1]
	v_cvt_pk_bf16_f32 v21, v22, v23
	global_store_dwordx2 v[30:31], v[20:21], off offset:1024
	v_sub_u32_e32 v20, v32, v55
	v_cvt_f32_i32_e32 v20, v20
	v_cmp_ge_i32_e64 s[0:1], v32, v55
	v_mul_f32_e32 v20, v68, v20
	v_mul_f32_e32 v20, 0x3fb8aa3b, v20
	v_exp_f32_e32 v20, v20
	s_nop 0
	v_mul_f32_e32 v16, v16, v20
	v_sub_u32_e32 v20, v32, v54
	v_cvt_f32_i32_e32 v20, v20
	v_cndmask_b32_e64 v16, 0, v16, s[0:1]
	v_cmp_ge_i32_e64 s[0:1], v32, v54
	v_mul_f32_e32 v20, v68, v20
	v_mul_f32_e32 v20, 0x3fb8aa3b, v20
	v_exp_f32_e32 v20, v20
	s_nop 0
	v_mul_f32_e32 v17, v17, v20
	v_sub_u32_e32 v20, v32, v49
	v_cvt_f32_i32_e32 v20, v20
	v_cndmask_b32_e64 v17, 0, v17, s[0:1]
	v_cmp_ge_i32_e64 s[0:1], v32, v49
	v_cvt_pk_bf16_f32 v16, v16, v17
	v_mul_f32_e32 v20, v68, v20
	v_mul_f32_e32 v20, 0x3fb8aa3b, v20
	v_exp_f32_e32 v20, v20
	s_nop 0
	v_mul_f32_e32 v18, v18, v20
	v_sub_u32_e32 v20, v32, v48
	v_cvt_f32_i32_e32 v20, v20
	v_cndmask_b32_e64 v18, 0, v18, s[0:1]
	v_cmp_ge_i32_e64 s[0:1], v32, v48
	v_mul_f32_e32 v20, v68, v20
	v_mul_f32_e32 v20, 0x3fb8aa3b, v20
	v_exp_f32_e32 v20, v20
	s_nop 0
	v_mul_f32_e32 v19, v19, v20
	v_cndmask_b32_e64 v19, 0, v19, s[0:1]
	v_cvt_pk_bf16_f32 v17, v18, v19
	global_store_dwordx2 v[30:31], v[16:17], off offset:1536
	v_or_b32_e32 v16, 48, v72
	v_sub_u32_e32 v17, v16, v71
	v_cvt_f32_i32_e32 v17, v17
	v_cmp_ge_i32_e64 s[0:1], v16, v71
	v_cmp_ge_i32_e32 vcc, v16, v54
	v_mul_f32_e32 v17, v68, v17
	v_mul_f32_e32 v17, 0x3fb8aa3b, v17
	v_exp_f32_e32 v17, v17
	s_nop 0
	v_mul_f32_e32 v12, v12, v17
	v_sub_u32_e32 v17, v16, v75
	v_cvt_f32_i32_e32 v17, v17
	v_cndmask_b32_e64 v12, 0, v12, s[0:1]
	v_cmp_gt_i32_e64 s[0:1], v16, v71
	v_mul_f32_e32 v17, v68, v17
	v_mul_f32_e32 v17, 0x3fb8aa3b, v17
	v_exp_f32_e32 v17, v17
	s_nop 0
	v_mul_f32_e32 v13, v13, v17
	v_sub_u32_e32 v17, v16, v73
	v_cvt_f32_i32_e32 v17, v17
	v_cndmask_b32_e64 v13, 0, v13, s[0:1]
	v_cmp_ge_i32_e64 s[0:1], v16, v73
	v_mul_f32_e32 v17, v68, v17
	v_mul_f32_e32 v17, 0x3fb8aa3b, v17
	v_exp_f32_e32 v17, v17
	s_nop 0
	v_mul_f32_e32 v14, v14, v17
	v_cndmask_b32_e64 v17, 0, v14, s[0:1]
	v_sub_u32_e32 v14, v16, v74
	v_cvt_f32_i32_e32 v14, v14
	v_cmp_ge_i32_e64 s[0:1], v16, v74
	v_mul_f32_e32 v14, v68, v14
	v_mul_f32_e32 v14, 0x3fb8aa3b, v14
	v_exp_f32_e32 v14, v14
	s_nop 0
	v_mul_f32_e32 v14, v15, v14
	v_cndmask_b32_e64 v15, 0, v14, s[0:1]
	v_cvt_pk_bf16_f32 v14, v12, v13
	v_lshlrev_b32_e32 v12, 7, v16
	v_and_b32_e32 v12, 0xfffff87f, v12
	v_ashrrev_i32_e32 v13, 31, v12
	v_lshlrev_b64 v[12:13], 1, v[12:13]
	v_or_b32_e32 v12, v12, v76
	v_lshl_add_u64 v[12:13], s[20:21], 0, v[12:13]
	v_add_co_u32_e64 v12, s[0:1], s34, v12
	v_cvt_pk_bf16_f32 v15, v17, v15
	s_nop 1
	v_addc_co_u32_e64 v13, s[0:1], 0, v13, s[0:1]
	global_store_dwordx2 v[12:13], v[14:15], off
	v_sub_u32_e32 v14, v16, v70
	v_cvt_f32_i32_e32 v14, v14
	v_cmp_ge_i32_e64 s[0:1], v16, v70
	v_mul_f32_e32 v14, v68, v14
	v_mul_f32_e32 v14, 0x3fb8aa3b, v14
	v_exp_f32_e32 v14, v14
	s_nop 0
	v_mul_f32_e32 v8, v8, v14
	v_sub_u32_e32 v14, v16, v61
	v_cvt_f32_i32_e32 v14, v14
	v_cndmask_b32_e64 v8, 0, v8, s[0:1]
	v_cmp_ge_i32_e64 s[0:1], v16, v61
	v_mul_f32_e32 v14, v68, v14
	v_mul_f32_e32 v14, 0x3fb8aa3b, v14
	v_exp_f32_e32 v14, v14
	s_nop 0
	v_mul_f32_e32 v9, v9, v14
	v_sub_u32_e32 v14, v16, v60
	v_cvt_f32_i32_e32 v14, v14
	v_cndmask_b32_e64 v9, 0, v9, s[0:1]
	v_cmp_ge_i32_e64 s[0:1], v16, v60
	v_cvt_pk_bf16_f32 v8, v8, v9
	v_mul_f32_e32 v14, v68, v14
	v_mul_f32_e32 v14, 0x3fb8aa3b, v14
	v_exp_f32_e32 v14, v14
	s_nop 0
	v_mul_f32_e32 v10, v10, v14
	v_sub_u32_e32 v14, v16, v58
	v_cvt_f32_i32_e32 v14, v14
	v_cndmask_b32_e64 v10, 0, v10, s[0:1]
	v_cmp_ge_i32_e64 s[0:1], v16, v58
	v_mul_f32_e32 v14, v68, v14
	v_mul_f32_e32 v14, 0x3fb8aa3b, v14
	v_exp_f32_e32 v14, v14
	s_nop 0
	v_mul_f32_e32 v11, v11, v14
	v_cndmask_b32_e64 v11, 0, v11, s[0:1]
	v_cvt_pk_bf16_f32 v9, v10, v11
	global_store_dwordx2 v[12:13], v[8:9], off offset:512
	v_sub_u32_e32 v8, v16, v57
	v_cvt_f32_i32_e32 v8, v8
	v_cmp_ge_i32_e64 s[0:1], v16, v57
	v_mul_f32_e32 v8, v68, v8
	v_mul_f32_e32 v8, 0x3fb8aa3b, v8
	v_exp_f32_e32 v8, v8
	s_nop 0
	v_mul_f32_e32 v4, v4, v8
	v_sub_u32_e32 v8, v16, v56
	v_cvt_f32_i32_e32 v8, v8
	v_cndmask_b32_e64 v4, 0, v4, s[0:1]
	v_cmp_ge_i32_e64 s[0:1], v16, v56
	v_mul_f32_e32 v8, v68, v8
	v_mul_f32_e32 v8, 0x3fb8aa3b, v8
	v_exp_f32_e32 v8, v8
	s_nop 0
	v_mul_f32_e32 v5, v5, v8
	v_sub_u32_e32 v8, v16, v53
	v_cvt_f32_i32_e32 v8, v8
	v_cndmask_b32_e64 v5, 0, v5, s[0:1]
	v_cmp_ge_i32_e64 s[0:1], v16, v53
	v_cvt_pk_bf16_f32 v4, v4, v5
	v_mul_f32_e32 v8, v68, v8
	v_mul_f32_e32 v8, 0x3fb8aa3b, v8
	v_exp_f32_e32 v8, v8
	s_nop 0
	v_mul_f32_e32 v6, v6, v8
	v_sub_u32_e32 v8, v16, v52
	v_cvt_f32_i32_e32 v8, v8
	v_cndmask_b32_e64 v6, 0, v6, s[0:1]
	v_cmp_ge_i32_e64 s[0:1], v16, v52
	v_mul_f32_e32 v8, v68, v8
	v_mul_f32_e32 v8, 0x3fb8aa3b, v8
	v_exp_f32_e32 v8, v8
	s_nop 0
	v_mul_f32_e32 v7, v7, v8
	v_cndmask_b32_e64 v7, 0, v7, s[0:1]
	v_cvt_pk_bf16_f32 v5, v6, v7
	global_store_dwordx2 v[12:13], v[4:5], off offset:1024
	v_sub_u32_e32 v4, v16, v54
	v_cvt_f32_i32_e32 v4, v4
	v_mul_f32_e32 v4, v68, v4
	v_mul_f32_e32 v4, 0x3fb8aa3b, v4
	v_exp_f32_e32 v4, v4
	s_nop 0
	v_mul_f32_e32 v1, v1, v4
	v_sub_u32_e32 v4, v16, v49
	v_cvt_f32_i32_e32 v4, v4
	v_cndmask_b32_e32 v1, 0, v1, vcc
	v_cmp_ge_i32_e32 vcc, v16, v49
	v_cvt_pk_bf16_f32 v0, v0, v1
	v_mul_f32_e32 v4, v68, v4
	v_mul_f32_e32 v4, 0x3fb8aa3b, v4
	v_exp_f32_e32 v4, v4
	s_nop 0
	v_mul_f32_e32 v2, v2, v4
	v_sub_u32_e32 v4, v16, v48
	v_cvt_f32_i32_e32 v4, v4
	v_cndmask_b32_e32 v2, 0, v2, vcc
	v_cmp_ge_i32_e32 vcc, v16, v48
	v_mul_f32_e32 v4, v68, v4
	v_mul_f32_e32 v4, 0x3fb8aa3b, v4
	v_exp_f32_e32 v4, v4
	s_nop 0
	v_mul_f32_e32 v3, v3, v4
	v_cndmask_b32_e32 v3, 0, v3, vcc
	v_cvt_pk_bf16_f32 v1, v2, v3
	global_store_dwordx2 v[12:13], v[0:1], off offset:1536
	s_cbranch_scc1 .LBB0_330

.LBB0_388:
	s_or_b64 exec, exec, s[4:5]
	s_and_b32 s43, s42, 3
	v_cvt_f32_ubyte0_e32 v0, s43
	v_sub_f32_e32 v0, 0xc0a00000, v0
	v_cmp_gt_f32_e32 vcc, s29, v0
	s_and_b32 s4, s40, 3
	s_lshl_b32 s9, s4, 10
	v_cndmask_b32_e32 v2, 0, v222, vcc
	s_and_b32 s4, s25, -16
	v_add_f32_e32 v0, v0, v2
	s_and_b32 s0, s41, 4
	s_ashr_i32 s5, s4, 31
	v_exp_f32_e32 v2, v0
	s_lshl_b32 s0, s0, 24
	s_lshl_b64 s[4:5], s[4:5], 1
	s_and_b32 s33, s42, 7
	s_lshl_b32 s46, s42, 1
	s_and_b64 s[44:45], vcc, exec
	s_cselect_b32 s43, 0xffffffc0, 0
	s_waitcnt vmcnt(48)
	v_ldexp_f32 v4, v2, s43
	v_sub_f32_e32 v5, 1.0, v4
	v_add_f32_e32 v2, -1.0, v5
	v_sub_f32_e32 v3, v2, v5
	v_add_f32_e32 v3, 1.0, v3
	v_sub_f32_e64 v2, -v4, v2
	v_add_f32_e32 v6, v2, v3
	v_frexp_mant_f32_e32 v7, v5
	v_cvt_f64_f32_e32 v[2:3], v5
	v_frexp_exp_i32_f64_e32 v2, v[2:3]
	v_cmp_gt_f32_e32 vcc, s30, v7
	s_lshl_b32 s43, s33, 23
	s_lshl_b32 s44, s33, 24
	v_subbrev_co_u32_e32 v2, vcc, 0, v2, vcc
	v_sub_u32_e32 v3, 0, v2
	v_ldexp_f32 v5, v5, v3
	v_ldexp_f32 v3, v6, v3
	v_add_f32_e32 v6, -1.0, v5
	v_add_f32_e32 v9, 1.0, v5
	v_add_f32_e32 v7, 1.0, v6
	v_add_f32_e32 v10, -1.0, v9
	v_sub_f32_e32 v7, v5, v7
	v_sub_f32_e32 v5, v5, v10
	v_add_f32_e32 v7, v3, v7
	v_add_f32_e32 v3, v3, v5
	v_add_f32_e32 v5, v9, v3
	v_rcp_f32_e32 v10, v5
	v_add_f32_e32 v8, v6, v7
	v_sub_f32_e32 v6, v8, v6
	v_sub_f32_e32 v6, v7, v6
	v_sub_f32_e32 v7, v5, v9
	v_sub_f32_e32 v3, v3, v7
	v_mul_f32_e32 v7, v8, v10
	v_mul_f32_e32 v9, v5, v7
	v_fma_f32 v11, v7, v5, -v9
	v_fmac_f32_e32 v11, v7, v3
	v_add_f32_e32 v12, v9, v11
	v_sub_f32_e32 v13, v8, v12
	v_sub_f32_e32 v8, v8, v13
	v_sub_f32_e32 v9, v12, v9
	v_sub_f32_e32 v8, v8, v12
	v_add_f32_e32 v6, v6, v8
	v_sub_f32_e32 v8, v9, v11
	v_add_f32_e32 v6, v8, v6
	v_add_f32_e32 v8, v13, v6
	v_mul_f32_e32 v9, v10, v8
	v_mul_f32_e32 v11, v5, v9
	v_fma_f32 v5, v9, v5, -v11
	v_fmac_f32_e32 v5, v9, v3
	v_sub_f32_e32 v3, v13, v8
	v_add_f32_e32 v3, v6, v3
	v_add_f32_e32 v6, v11, v5
	v_sub_f32_e32 v12, v8, v6
	v_sub_f32_e32 v8, v8, v12
	v_sub_f32_e32 v11, v6, v11
	v_sub_f32_e32 v6, v8, v6
	v_add_f32_e32 v3, v3, v6
	v_sub_f32_e32 v5, v11, v5
	v_cvt_f32_i32_e32 v2, v2
	v_add_f32_e32 v3, v5, v3
	v_add_f32_e32 v5, v7, v9
	v_add_f32_e32 v3, v12, v3
	v_sub_f32_e32 v6, v5, v7
	v_mul_f32_e32 v3, v10, v3
	v_sub_f32_e32 v6, v9, v6
	v_add_f32_e32 v3, v6, v3
	v_mul_f32_e32 v9, 0x3f317218, v2
	v_add_f32_e32 v6, v5, v3
	v_fma_f32 v10, v2, s31, -v9
	v_mul_f32_e32 v7, v6, v6
	v_fmac_f32_e32 v10, 0xb102e308, v2
	v_sub_f32_e32 v2, v6, v5
	v_fmamk_f32 v8, v7, 0x3e9b6dac, v223
	v_sub_f32_e32 v2, v3, v2
	v_add_f32_e32 v3, v9, v10
	v_fmaak_f32 v8, v7, v8, 0x3f2aaada
	v_sub_f32_e32 v5, v3, v9
	v_ldexp_f32 v9, v6, 1
	v_mul_f32_e32 v6, v6, v7
	v_mul_f32_e32 v6, v6, v8
	v_add_f32_e32 v7, v9, v6
	v_sub_f32_e32 v8, v7, v9
	v_ldexp_f32 v2, v2, 1
	v_sub_f32_e32 v6, v6, v8
	v_add_f32_e32 v2, v2, v6
	v_add_f32_e32 v6, v7, v2
	v_sub_f32_e32 v7, v6, v7
	v_sub_f32_e32 v2, v2, v7
	v_add_f32_e32 v7, v3, v6
	v_sub_f32_e32 v8, v7, v3
	v_sub_f32_e32 v9, v7, v8
	v_sub_f32_e32 v5, v10, v5
	v_sub_f32_e32 v3, v3, v9
	v_sub_f32_e32 v6, v6, v8
	v_add_f32_e32 v3, v6, v3
	v_add_f32_e32 v6, v5, v2
	v_sub_f32_e32 v8, v6, v5
	v_sub_f32_e32 v9, v6, v8
	v_sub_f32_e32 v5, v5, v9
	v_sub_f32_e32 v2, v2, v8
	v_add_f32_e32 v3, v6, v3
	v_add_f32_e32 v2, v2, v5
	v_add_f32_e32 v5, v7, v3
	v_sub_f32_e32 v6, v5, v7
	v_sub_f32_e32 v3, v3, v6
	v_add_f32_e32 v2, v2, v3
	v_add_f32_e32 v2, v5, v2
	v_cmp_nlt_f32_e32 vcc, 1.0, v4
	s_add_u32 s44, s15, s44
	s_addc_u32 s45, s16, 0
	v_cndmask_b32_e32 v2, v224, v2, vcc
	v_cmp_neq_f32_e32 vcc, 1.0, v4
	s_lshl_b32 s33, s33, 22
	v_and_b32_e32 v181, 15, v1
	v_cndmask_b32_e32 v2, v225, v2, vcc
	v_cmp_gt_f32_e32 vcc, s34, v4
	v_bfe_u32 v182, v1, 4, 2
	v_lshlrev_b32_e32 v192, 4, v182
	v_lshlrev_b32_e32 v255, 8, v182
	v_lshl_or_b32 v255, v181, 4, v255
	v_cndmask_b32_e64 v183, v2, -v4, vcc
	v_mul_f32_e32 v2, 0x43000000, v183
	v_mul_f32_e32 v2, 0x3fb8aa3b, v2
	v_exp_f32_e32 v194, v2
	s_and_b32 s100, s46, -16
	s_lshl_b32 s100, s100, 8
	v_add_u32_e32 v2, s100, v255
	v_mov_b32_e32 v3, 0
	v_lshl_add_u64 v[2:3], s[44:45], 0, v[2:3]
	s_add_u32 s44, s17, s43
	s_addc_u32 s45, s22, 0
	s_add_u32 s46, s3, s43
	v_ashrrev_i32_e32 v4, 1, v1
	s_addc_u32 s47, s14, 0
	s_waitcnt vmcnt(44)
	v_and_b32_e32 v20, 0xffffffe0, v4
	s_add_u32 s48, s23, s33
	s_addc_u32 s49, s24, 0
	v_ashrrev_i32_e32 v199, 31, v20
	v_or_b32_e32 v198, v20, v181
	v_lshl_or_b32 v180, v182, 2, v20
	v_mov_b64_e32 v[196:197], v[2:3]
	v_mov_b32_e32 v2, v255
	v_mov_b32_e32 v3, 0
	v_lshl_add_u64 v[200:201], s[48:49], 0, v[2:3]
	v_and_b32_e32 v2, -16, v198
	v_mov_b32_e32 v3, 0
	v_lshlrev_b64 v[2:3], 8, v[2:3]
	v_or_b32_e32 v4, 1, v180
	v_lshl_add_u64 v[2:3], v[200:201], 0, v[2:3]
	s_waitcnt vmcnt(36)
	v_ashrrev_i32_e32 v25, 31, v198
	v_and_b32_e32 v24, -16, v198
	s_waitcnt lgkmcnt(0)
	s_barrier
	v_cvt_f32_i32_e32 v184, v4
	global_load_dwordx4 v[16:19], v[196:197], off
	global_load_dwordx4 v[12:15], v[196:197], off offset:1024
	global_load_dwordx4 v[8:11], v[196:197], off offset:2048
	global_load_dwordx4 v[4:7], v[196:197], off offset:3072
	v_add_u32_e32 v202, 0x1000, v255
	v_mov_b32_e32 v203, s45
	v_add_co_u32_e32 v202, vcc, s44, v202
	s_nop 1
	v_addc_co_u32_e32 v203, vcc, 0, v203, vcc
	global_load_dwordx4 v[136:139], v[2:3], off
	global_load_dwordx4 v[52:55], v[2:3], off offset:1024
	global_load_dwordx4 v[32:35], v[2:3], off offset:2048
	global_load_dwordx4 v[20:23], v[2:3], off offset:3072
	v_lshlrev_b64 v[24:25], 9, v[24:25]
	v_add_co_u32_e32 v2, vcc, s35, v2
	v_lshl_add_u64 v[24:25], v[202:203], 0, v[24:25]
	s_nop 0
	v_addc_co_u32_e32 v3, vcc, 0, v3, vcc
	global_load_dwordx4 v[60:63], v[24:25], off offset:-4096
	global_load_dwordx4 v[56:59], v[24:25], off offset:-3072
	global_load_dwordx4 v[48:51], v[24:25], off offset:-2048
	global_load_dwordx4 v[44:47], v[24:25], off offset:-1024
	global_load_dwordx4 v[40:43], v[24:25], off
	global_load_dwordx4 v[36:39], v[24:25], off offset:1024
	global_load_dwordx4 v[28:31], v[24:25], off offset:2048
	s_nop 0
	global_load_dwordx4 v[24:27], v[24:25], off offset:3072
	s_nop 0
	global_load_dwordx4 v[164:167], v[2:3], off
	global_load_dwordx4 v[92:95], v[2:3], off offset:1024
	global_load_dwordx4 v[68:71], v[2:3], off offset:2048
	global_load_dwordx4 v[64:67], v[2:3], off offset:3072
	v_and_b32_e32 v2, -16, v198
	v_or_b32_e32 v2, 16, v2
	v_ashrrev_i32_e32 v3, 31, v2
	s_waitcnt vmcnt(28)
	v_lshlrev_b32_e32 v144, 7, v1
	v_lshlrev_b64 v[2:3], 9, v[2:3]
	v_and_b32_e32 v206, 0xffffe000, v144
	v_lshl_add_u64 v[2:3], v[202:203], 0, v[2:3]
	v_mov_b32_e32 v205, s47
	v_add_co_u32_e32 v204, vcc, s46, v255
	s_nop 1
	v_addc_co_u32_e32 v205, vcc, 0, v205, vcc
	v_ashrrev_i32_e32 v207, 31, v206
	v_or_b32_e32 v208, 0x800, v206
	global_load_dwordx4 v[104:107], v[2:3], off offset:-4096
	global_load_dwordx4 v[100:103], v[2:3], off offset:-3072
	global_load_dwordx4 v[96:99], v[2:3], off offset:-2048
	global_load_dwordx4 v[88:91], v[2:3], off offset:-1024
	global_load_dwordx4 v[84:87], v[2:3], off
	global_load_dwordx4 v[80:83], v[2:3], off offset:1024
	global_load_dwordx4 v[76:79], v[2:3], off offset:2048
	global_load_dwordx4 v[72:75], v[2:3], off offset:3072
	v_lshl_add_u64 v[2:3], v[206:207], 1, v[204:205]
	v_ashrrev_i32_e32 v209, 31, v208
	v_or_b32_e32 v210, 0x1000, v206
	global_load_dwordx4 v[176:179], v[2:3], off
	global_load_dwordx4 v[120:123], v[2:3], off offset:1024
	global_load_dwordx4 v[112:115], v[2:3], off offset:2048
	global_load_dwordx4 v[108:111], v[2:3], off offset:3072
	v_lshl_add_u64 v[2:3], v[208:209], 1, v[204:205]
	v_ashrrev_i32_e32 v211, 31, v210
	v_or_b32_e32 v212, 0x1800, v206
	global_load_dwordx4 v[172:175], v[2:3], off
	global_load_dwordx4 v[132:135], v[2:3], off offset:1024
	global_load_dwordx4 v[124:127], v[2:3], off offset:2048
	global_load_dwordx4 v[116:119], v[2:3], off offset:3072
	v_lshl_add_u64 v[2:3], v[210:211], 1, v[204:205]
	v_ashrrev_i32_e32 v213, 31, v212
	global_load_dwordx4 v[168:171], v[2:3], off
	global_load_dwordx4 v[148:151], v[2:3], off offset:1024
	global_load_dwordx4 v[140:143], v[2:3], off offset:2048
	global_load_dwordx4 v[128:131], v[2:3], off offset:3072
	v_lshl_add_u64 v[2:3], v[212:213], 1, v[204:205]
	global_load_dwordx4 v[160:163], v[2:3], off
	global_load_dwordx4 v[156:159], v[2:3], off offset:1024
	global_load_dwordx4 v[152:155], v[2:3], off offset:2048
	global_load_dwordx4 v[144:147], v[2:3], off offset:3072
	v_or_b32_e32 v2, 2, v180
	v_cvt_f32_i32_e32 v2, v2
	v_mul_f32_e32 v3, v183, v184
	v_mul_f32_e32 v3, 0x3fb8aa3b, v3
	v_exp_f32_e32 v227, v3
	v_mul_f32_e32 v2, v183, v2
	v_mul_f32_e32 v2, 0x3fb8aa3b, v2
	v_exp_f32_e32 v228, v2
	v_add_u32_e32 v2, 4, v180
	v_or_b32_e32 v3, 3, v180
	v_cvt_f32_i32_e32 v2, v2
	v_cvt_f32_i32_e32 v3, v3
	s_add_u32 s4, s4, s9
	s_addc_u32 s5, s5, 0
	v_mul_f32_e32 v2, v183, v2
	v_mul_f32_e32 v3, v183, v3
	v_mul_f32_e32 v2, 0x3fb8aa3b, v2
	v_mul_f32_e32 v3, 0x3fb8aa3b, v3
	v_exp_f32_e32 v230, v2
	v_or_b32_e32 v2, 18, v180
	v_exp_f32_e32 v229, v3
	v_or_b32_e32 v3, 17, v180
	v_cvt_f32_i32_e32 v2, v2
	v_cvt_f32_i32_e32 v3, v3
	s_add_u32 s4, s4, s0
	v_and_b32_e32 v1, 0x7fffffc0, v1
	v_mul_f32_e32 v2, v183, v2
	v_mul_f32_e32 v3, v183, v3
	v_mul_f32_e32 v2, 0x3fb8aa3b, v2
	v_mul_f32_e32 v3, 0x3fb8aa3b, v3
	v_exp_f32_e32 v232, v2
	v_add_u32_e32 v2, 20, v180
	v_exp_f32_e32 v231, v3
	v_or_b32_e32 v3, 19, v180
	v_cvt_f32_i32_e32 v2, v2
	v_cvt_f32_i32_e32 v3, v3
	s_addc_u32 s5, s5, 0
	v_lshlrev_b32_e32 v1, 1, v1
	v_mul_f32_e32 v2, v183, v2
	v_mul_f32_e32 v3, v183, v3
	v_mul_f32_e32 v2, 0x3fb8aa3b, v2
	v_mul_f32_e32 v3, 0x3fb8aa3b, v3
	v_exp_f32_e32 v234, v2
	v_or_b32_e32 v2, 16, v180
	v_exp_f32_e32 v233, v3
	v_ashrrev_i32_e32 v3, 31, v2
	v_lshlrev_b64 v[2:3], 12, v[2:3]
	v_lshl_add_u64 v[2:3], s[4:5], 0, v[2:3]
	v_lshlrev_b32_e32 v184, 1, v181
	v_mul_u32_u24_e32 v183, 0x210, v181
	v_mad_u32_u24 v1, v181, s36, v1
	v_or_b32_e32 v2, v2, v184
	v_ashrrev_i32_e32 v181, 31, v180
	v_lshl_add_u64 v[216:217], s[70:71], 0, v[2:3]
	v_lshlrev_b64 v[2:3], 12, v[180:181]
	v_lshl_add_u64 v[2:3], s[4:5], 0, v[2:3]
	v_mov_b32_e32 v0, 0
	v_lshlrev_b32_e32 v182, 3, v182
	v_or_b32_e32 v2, v2, v184
	s_mov_b32 s8, 1
	v_mov_b32_e32 v214, v194
	v_mov_b32_e32 v215, v194
	v_lshl_add_u64 v[218:219], s[70:71], 0, v[2:3]
	s_mov_b64 s[4:5], 0
	v_add_u32_e32 v192, v183, v192
	v_add_u32_e32 v235, v1, v182
	v_mov_b32_e32 v1, v0
	v_mov_b32_e32 v2, v0
	v_mov_b32_e32 v3, v0
	v_mov_b32_e32 v188, v0
	v_mov_b32_e32 v189, v0
	v_mov_b32_e32 v190, v0
	v_mov_b32_e32 v191, v0
	v_mov_b32_e32 v184, v0
	v_mov_b32_e32 v185, v0
	v_mov_b32_e32 v186, v0
	v_mov_b32_e32 v187, v0
	v_mov_b32_e32 v180, v0
	v_mov_b32_e32 v181, v0
	v_mov_b32_e32 v182, v0
	v_mov_b32_e32 v183, v0
.LBB0_389:
	v_mov_b32_e32 v195, v194
	s_waitcnt vmcnt(39)
	v_mfma_f32_16x16x32_bf16 v[136:139], v[136:139], v[16:19], 0
	v_mul_f32_e64 v0, v214, v0
	v_mul_f32_e64 v1, v215, v1
	v_pk_mul_f32 v[2:3], v[194:195], v[2:3]
	s_waitcnt vmcnt(27)
	v_mfma_f32_16x16x32_bf16 v[164:167], v[164:167], v[16:19], 0
	s_waitcnt vmcnt(15)
	v_mfma_f32_16x16x32_bf16 v[0:3], v[176:179], v[16:19], v[0:3]
	v_mul_f32_e64 v176, v214, v188
	v_mul_f32_e64 v177, v215, v189
	v_pk_mul_f32 v[178:179], v[194:195], v[190:191]
	v_mfma_f32_16x16x32_bf16 v[52:55], v[52:55], v[12:15], v[136:139]
	s_waitcnt vmcnt(11)
	v_mfma_f32_16x16x32_bf16 v[172:175], v[172:175], v[16:19], v[176:179]
	s_nop 2
	v_mul_f32_e64 v176, v214, v184
	v_mul_f32_e64 v177, v215, v185
	v_pk_mul_f32 v[178:179], v[194:195], v[186:187]
	v_mfma_f32_16x16x32_bf16 v[92:95], v[92:95], v[12:15], v[164:167]
	s_waitcnt vmcnt(7)
	v_mfma_f32_16x16x32_bf16 v[168:171], v[168:171], v[16:19], v[176:179]
	s_nop 2
	v_mul_f32_e64 v176, v214, v180
	v_mul_f32_e64 v177, v215, v181
	v_pk_mul_f32 v[178:179], v[194:195], v[182:183]
	v_mfma_f32_16x16x32_bf16 v[0:3], v[120:123], v[12:15], v[0:3]
	s_waitcnt vmcnt(3)
	v_mfma_f32_16x16x32_bf16 v[16:19], v[160:163], v[16:19], v[176:179]
	ds_read_b128 v[136:139], v192
	ds_read_b128 v[160:163], v192 offset:64
	s_waitcnt lgkmcnt(1)
	v_mfma_f32_16x16x32_bf16 v[60:63], v[60:63], v[136:139], 0
	v_mfma_f32_16x16x32_bf16 v[104:107], v[104:107], v[136:139], 0
	v_mfma_f32_16x16x32_bf16 v[120:123], v[132:135], v[12:15], v[172:175]
	v_mfma_f32_16x16x32_bf16 v[132:135], v[148:151], v[12:15], v[168:171]
	s_waitcnt vmcnt(2)
	v_mfma_f32_16x16x32_bf16 v[12:15], v[156:159], v[12:15], v[16:19]
	v_mfma_f32_16x16x32_bf16 v[16:19], v[32:35], v[8:11], v[52:55]
	v_mfma_f32_16x16x32_bf16 v[32:35], v[68:71], v[8:11], v[92:95]
	s_waitcnt lgkmcnt(0)
	v_mfma_f32_16x16x32_bf16 v[52:55], v[56:59], v[160:163], v[60:63]
	v_mfma_f32_16x16x32_bf16 v[56:59], v[100:103], v[160:163], v[104:107]
	v_mfma_f32_16x16x32_bf16 v[0:3], v[112:115], v[8:11], v[0:3]
	v_mfma_f32_16x16x32_bf16 v[60:63], v[124:127], v[8:11], v[120:123]
	v_mfma_f32_16x16x32_bf16 v[68:71], v[140:143], v[8:11], v[132:135]
	s_waitcnt vmcnt(1)
	v_mfma_f32_16x16x32_bf16 v[8:11], v[152:155], v[8:11], v[12:15]
	v_mfma_f32_16x16x32_bf16 v[236:239], v[20:23], v[4:7], v[16:19]
	s_nop 1
	ds_read_b128 v[12:15], v192 offset:128
	ds_read_b128 v[16:19], v192 offset:192
	s_waitcnt lgkmcnt(1)
	v_mfma_f32_16x16x32_bf16 v[20:23], v[48:51], v[12:15], v[52:55]
	v_mfma_f32_16x16x32_bf16 v[12:15], v[96:99], v[12:15], v[56:59]
	v_mfma_f32_16x16x32_bf16 v[240:243], v[64:67], v[4:7], v[32:35]
	v_mfma_f32_16x16x32_bf16 v[0:3], v[108:111], v[4:7], v[0:3]
	v_mfma_f32_16x16x32_bf16 v[188:191], v[116:119], v[4:7], v[60:63]
	v_mfma_f32_16x16x32_bf16 v[184:187], v[128:131], v[4:7], v[68:71]
	s_waitcnt vmcnt(0)
	v_mfma_f32_16x16x32_bf16 v[180:183], v[144:147], v[4:7], v[8:11]
	s_waitcnt lgkmcnt(0)
	v_mfma_f32_16x16x32_bf16 v[4:7], v[44:47], v[16:19], v[20:23]
	v_mfma_f32_16x16x32_bf16 v[8:11], v[88:91], v[16:19], v[12:15]
	s_nop 2
	ds_read_b128 v[12:15], v192 offset:256
	ds_read_b128 v[16:19], v192 offset:320
	s_waitcnt lgkmcnt(1)
	v_mfma_f32_16x16x32_bf16 v[4:7], v[40:43], v[12:15], v[4:7]
	v_mfma_f32_16x16x32_bf16 v[8:11], v[84:87], v[12:15], v[8:11]
	s_waitcnt lgkmcnt(0)
	v_mfma_f32_16x16x32_bf16 v[4:7], v[36:39], v[16:19], v[4:7]
	v_mfma_f32_16x16x32_bf16 v[8:11], v[80:83], v[16:19], v[8:11]
	ds_read_b128 v[12:15], v192 offset:384
	ds_read_b128 v[16:19], v192 offset:448
	s_waitcnt lgkmcnt(1)
	v_mfma_f32_16x16x32_bf16 v[4:7], v[28:31], v[12:15], v[4:7]
	v_mfma_f32_16x16x32_bf16 v[8:11], v[76:79], v[12:15], v[8:11]
	s_waitcnt lgkmcnt(0)
	v_mfma_f32_16x16x32_bf16 v[244:247], v[24:27], v[16:19], v[4:7]
	v_mfma_f32_16x16x32_bf16 v[248:251], v[72:75], v[16:19], v[8:11]
	s_min_i32 s9, s8, 0x7f
	s_lshl_b32 s0, s9, 17
	s_nop 1
	v_lshl_add_u64 v[4:5], v[196:197], 0, s[0:1]
	s_lshl_b32 s0, s9, 7
	v_and_b32_e32 v72, -16, v198
	v_add_u32_e32 v72, s0, v72
	v_and_b32_e32 v20, -16, v198
	v_mov_b32_e32 v21, 0
	v_lshl_add_u64 v[20:21], v[20:21], 0, s[0:1]
	v_ashrrev_i32_e32 v73, 31, v72
	v_lshlrev_b64 v[20:21], 8, v[20:21]
	v_lshlrev_b64 v[24:25], 9, v[72:73]
	v_or_b32_e32 v72, 16, v72
	v_lshl_add_u64 v[64:65], v[200:201], 0, v[20:21]
	v_ashrrev_i32_e32 v73, 31, v72
	global_load_dwordx4 v[16:19], v[4:5], off
	global_load_dwordx4 v[12:15], v[4:5], off offset:1024
	global_load_dwordx4 v[8:11], v[4:5], off offset:2048
	s_nop 0
	global_load_dwordx4 v[4:7], v[4:5], off offset:3072
	s_nop 0
	global_load_dwordx4 v[136:139], v[64:65], off
	global_load_dwordx4 v[52:55], v[64:65], off offset:1024
	global_load_dwordx4 v[32:35], v[64:65], off offset:2048
	global_load_dwordx4 v[20:23], v[64:65], off offset:3072
	v_add_co_u32_e32 v64, vcc, s35, v64
	v_lshlrev_b64 v[72:73], 9, v[72:73]
	v_lshl_add_u64 v[24:25], v[202:203], 0, v[24:25]
	v_addc_co_u32_e32 v65, vcc, 0, v65, vcc
	v_lshl_add_u64 v[72:73], v[202:203], 0, v[72:73]
	global_load_dwordx4 v[60:63], v[24:25], off offset:-4096
	global_load_dwordx4 v[56:59], v[24:25], off offset:-3072
	global_load_dwordx4 v[48:51], v[24:25], off offset:-2048
	global_load_dwordx4 v[44:47], v[24:25], off offset:-1024
	global_load_dwordx4 v[40:43], v[24:25], off
	global_load_dwordx4 v[36:39], v[24:25], off offset:1024
	global_load_dwordx4 v[28:31], v[24:25], off offset:2048
	s_nop 0
	global_load_dwordx4 v[24:27], v[24:25], off offset:3072
	s_nop 0
	global_load_dwordx4 v[164:167], v[64:65], off
	global_load_dwordx4 v[92:95], v[64:65], off offset:1024
	global_load_dwordx4 v[68:71], v[64:65], off offset:2048
	s_nop 0
	global_load_dwordx4 v[64:67], v[64:65], off offset:3072
	s_nop 0
	global_load_dwordx4 v[104:107], v[72:73], off offset:-4096
	global_load_dwordx4 v[100:103], v[72:73], off offset:-3072
	global_load_dwordx4 v[96:99], v[72:73], off offset:-2048
	global_load_dwordx4 v[88:91], v[72:73], off offset:-1024
	global_load_dwordx4 v[84:87], v[72:73], off
	global_load_dwordx4 v[80:83], v[72:73], off offset:1024
	global_load_dwordx4 v[76:79], v[72:73], off offset:2048
	s_nop 0
	global_load_dwordx4 v[72:75], v[72:73], off offset:3072
	s_lshl_b32 s0, s9, 16
	v_lshl_add_u64 v[144:145], v[204:205], 0, s[0:1]
	v_lshl_add_u64 v[108:109], v[206:207], 1, v[144:145]
	v_lshl_add_u64 v[116:117], v[208:209], 1, v[144:145]
	v_lshl_add_u64 v[128:129], v[210:211], 1, v[144:145]
	v_lshl_add_u64 v[144:145], v[212:213], 1, v[144:145]
	global_load_dwordx4 v[176:179], v[108:109], off
	global_load_dwordx4 v[120:123], v[108:109], off offset:1024
	global_load_dwordx4 v[112:115], v[108:109], off offset:2048
	s_nop 0
	global_load_dwordx4 v[108:111], v[108:109], off offset:3072
	s_nop 0
	global_load_dwordx4 v[172:175], v[116:117], off
	global_load_dwordx4 v[132:135], v[116:117], off offset:1024
	global_load_dwordx4 v[124:127], v[116:117], off offset:2048
	s_nop 0
	global_load_dwordx4 v[116:119], v[116:117], off offset:3072
	s_nop 0
	global_load_dwordx4 v[168:171], v[128:129], off
	global_load_dwordx4 v[148:151], v[128:129], off offset:1024
	global_load_dwordx4 v[140:143], v[128:129], off offset:2048
	s_nop 0
	global_load_dwordx4 v[128:131], v[128:129], off offset:3072
	s_nop 0
	global_load_dwordx4 v[160:163], v[144:145], off
	global_load_dwordx4 v[156:159], v[144:145], off offset:1024
	global_load_dwordx4 v[152:155], v[144:145], off offset:2048
	s_nop 0
	global_load_dwordx4 v[144:147], v[144:145], off offset:3072
	v_fma_f32 v195, v227, v244, v236
	v_bfe_u32 v236, v195, 16, 1
	v_add3_u32 v195, v195, v236, s37
	v_lshl_add_u64 v[252:253], v[218:219], 0, s[4:5]
	global_store_short_d16_hi v[252:253], v195, off
	v_fma_f32 v195, v228, v245, v237
	v_bfe_u32 v236, v195, 16, 1
	v_add3_u32 v195, v195, v236, s37
	v_add_co_u32_e32 v236, vcc, s38, v252
	v_fmac_f32_e32 v239, v230, v247
	s_nop 0
	v_addc_co_u32_e32 v237, vcc, 0, v253, vcc
	global_store_short_d16_hi v[236:237], v195, off offset:-4096
	v_fma_f32 v195, v229, v246, v238
	v_bfe_u32 v238, v195, 16, 1
	v_add3_u32 v195, v195, v238, s37
	global_store_short_d16_hi v[236:237], v195, off
	v_bfe_u32 v195, v239, 16, 1
	v_add_co_u32_e32 v236, vcc, s39, v252
	v_add3_u32 v195, v239, v195, s37
	s_nop 0
	v_addc_co_u32_e32 v237, vcc, 0, v253, vcc
	global_store_short_d16_hi v[236:237], v195, off
	v_fma_f32 v195, v231, v248, v240
	v_bfe_u32 v236, v195, 16, 1
	v_add3_u32 v195, v195, v236, s37
	v_lshl_add_u64 v[236:237], v[216:217], 0, s[4:5]
	global_store_short_d16_hi v[236:237], v195, off
	v_fma_f32 v195, v232, v249, v241
	v_bfe_u32 v238, v195, 16, 1
	v_add3_u32 v195, v195, v238, s37
	v_add_co_u32_e32 v238, vcc, s38, v236
	v_fmac_f32_e32 v243, v234, v251
	s_nop 0
	v_addc_co_u32_e32 v239, vcc, 0, v237, vcc
	global_store_short_d16_hi v[238:239], v195, off offset:-4096
	v_fma_f32 v195, v233, v250, v242
	v_bfe_u32 v240, v195, 16, 1
	v_add3_u32 v195, v195, v240, s37
	global_store_short_d16_hi v[238:239], v195, off
	v_bfe_u32 v195, v243, 16, 1
	v_add_co_u32_e32 v236, vcc, s39, v236
	v_add3_u32 v195, v243, v195, s37
	s_nop 0
	v_addc_co_u32_e32 v237, vcc, 0, v237, vcc
	global_store_short_d16_hi v[236:237], v195, off
	v_and_b32_sdwa v237, v3, v226 dst_sel:DWORD dst_unused:UNUSED_PAD src0_sel:WORD_1 src1_sel:DWORD
	v_and_b32_sdwa v238, v1, v226 dst_sel:DWORD dst_unused:UNUSED_PAD src0_sel:WORD_1 src1_sel:DWORD
	v_and_b32_sdwa v195, v2, v226 dst_sel:DWORD dst_unused:UNUSED_PAD src0_sel:WORD_1 src1_sel:DWORD
	v_and_b32_sdwa v236, v0, v226 dst_sel:DWORD dst_unused:UNUSED_PAD src0_sel:WORD_1 src1_sel:DWORD
	v_add3_u32 v237, v3, v237, s37
	v_add3_u32 v238, v1, v238, s37
	v_add3_u32 v236, v0, v236, s37
	v_add3_u32 v195, v2, v195, s37
	v_and_b32_e32 v237, 0xffff0000, v237
	v_and_b32_e32 v238, 0xffff0000, v238
	v_and_b32_sdwa v239, v191, v226 dst_sel:DWORD dst_unused:UNUSED_PAD src0_sel:WORD_1 src1_sel:DWORD
	v_and_b32_sdwa v240, v189, v226 dst_sel:DWORD dst_unused:UNUSED_PAD src0_sel:WORD_1 src1_sel:DWORD
	v_or_b32_sdwa v237, v237, v195 dst_sel:DWORD dst_unused:UNUSED_PAD src0_sel:DWORD src1_sel:WORD_1
	v_or_b32_sdwa v236, v238, v236 dst_sel:DWORD dst_unused:UNUSED_PAD src0_sel:DWORD src1_sel:WORD_1
	v_and_b32_sdwa v195, v190, v226 dst_sel:DWORD dst_unused:UNUSED_PAD src0_sel:WORD_1 src1_sel:DWORD
	v_and_b32_sdwa v238, v188, v226 dst_sel:DWORD dst_unused:UNUSED_PAD src0_sel:WORD_1 src1_sel:DWORD
	v_add3_u32 v239, v191, v239, s37
	v_add3_u32 v240, v189, v240, s37
	v_add3_u32 v238, v188, v238, s37
	v_add3_u32 v195, v190, v195, s37
	v_and_b32_e32 v239, 0xffff0000, v239
	v_and_b32_e32 v240, 0xffff0000, v240
	v_or_b32_sdwa v239, v239, v195 dst_sel:DWORD dst_unused:UNUSED_PAD src0_sel:DWORD src1_sel:WORD_1
	v_or_b32_sdwa v238, v240, v238 dst_sel:DWORD dst_unused:UNUSED_PAD src0_sel:DWORD src1_sel:WORD_1
	s_waitcnt lgkmcnt(0)
	s_barrier
	ds_write2_b64 v235, v[236:237], v[238:239] offset1:4
	v_and_b32_sdwa v237, v187, v226 dst_sel:DWORD dst_unused:UNUSED_PAD src0_sel:WORD_1 src1_sel:DWORD
	v_and_b32_sdwa v238, v185, v226 dst_sel:DWORD dst_unused:UNUSED_PAD src0_sel:WORD_1 src1_sel:DWORD
	v_and_b32_sdwa v195, v186, v226 dst_sel:DWORD dst_unused:UNUSED_PAD src0_sel:WORD_1 src1_sel:DWORD
	v_and_b32_sdwa v236, v184, v226 dst_sel:DWORD dst_unused:UNUSED_PAD src0_sel:WORD_1 src1_sel:DWORD
	v_add3_u32 v237, v187, v237, s37
	v_add3_u32 v238, v185, v238, s37
	v_add3_u32 v236, v184, v236, s37
	v_add3_u32 v195, v186, v195, s37
	v_and_b32_e32 v237, 0xffff0000, v237
	v_and_b32_e32 v238, 0xffff0000, v238
	v_and_b32_sdwa v239, v183, v226 dst_sel:DWORD dst_unused:UNUSED_PAD src0_sel:WORD_1 src1_sel:DWORD
	v_and_b32_sdwa v240, v181, v226 dst_sel:DWORD dst_unused:UNUSED_PAD src0_sel:WORD_1 src1_sel:DWORD
	v_or_b32_sdwa v237, v237, v195 dst_sel:DWORD dst_unused:UNUSED_PAD src0_sel:DWORD src1_sel:WORD_1
	v_or_b32_sdwa v236, v238, v236 dst_sel:DWORD dst_unused:UNUSED_PAD src0_sel:DWORD src1_sel:WORD_1
	v_and_b32_sdwa v195, v182, v226 dst_sel:DWORD dst_unused:UNUSED_PAD src0_sel:WORD_1 src1_sel:DWORD
	v_and_b32_sdwa v238, v180, v226 dst_sel:DWORD dst_unused:UNUSED_PAD src0_sel:WORD_1 src1_sel:DWORD
	v_add3_u32 v239, v183, v239, s37
	v_add3_u32 v240, v181, v240, s37
	v_add3_u32 v238, v180, v238, s37
	v_add3_u32 v195, v182, v195, s37
	v_and_b32_e32 v239, 0xffff0000, v239
	v_and_b32_e32 v240, 0xffff0000, v240
	v_or_b32_sdwa v239, v239, v195 dst_sel:DWORD dst_unused:UNUSED_PAD src0_sel:DWORD src1_sel:WORD_1
	v_or_b32_sdwa v238, v240, v238 dst_sel:DWORD dst_unused:UNUSED_PAD src0_sel:DWORD src1_sel:WORD_1
	ds_write2_b64 v235, v[236:237], v[238:239] offset0:8 offset1:12
	s_waitcnt lgkmcnt(0)
	s_barrier
	s_add_u32 s4, s4, 0x80000
	s_addc_u32 s5, s5, 0
	s_add_i32 s8, s8, 1
	s_cmp_lg_u32 s4, 0x4000000
	s_cbranch_scc1 .LBB0_389
	s_add_i32 s42, s42, s74
	s_add_i32 s41, s41, s74
	s_add_i32 s40, s40, s74
	s_add_i32 s25, s25, s26
	s_cmpk_lt_i32 s42, 0x100
	s_cbranch_scc1 .LBB0_385
